# LDS read bases as one biased VGPR + immediate offsets and m0 wait states filled with ds_reads also in the P1 (bf16, int8) and P4 K-loops
# speedup vs baseline: 1.0090x; 1.0074x over previous
.LBB0_200:
	s_and_b32 s16, s10, 3
	s_lshl_b32 s54, s11, 6
	s_lshl_b32 s15, s11, 13
	s_mov_b64 s[10:11], 0x80
	s_add_i32 m0, s49, 0x18000
	v_lshl_add_u64 v[8:9], v[8:9], 0, s[10:11]
	s_lshl_b32 s55, s16, 5
	s_lshl_b32 s17, s16, 12
	s_waitcnt vmcnt(2)
	s_barrier
	global_load_lds_dwordx4 v[8:9], off
	v_lshl_add_u64 v[6:7], v[6:7], 0, s[10:11]
	s_add_i32 m0, s49, 0x1a000
	s_add_i32 s56, s49, 0x8000
	s_add_i32 s57, s49, 0xa000
	global_load_lds_dwordx4 v[6:7], off
	v_lshl_add_u64 v[0:1], v[0:1], 0, s[10:11]
	s_mov_b32 m0, s56
	s_add_u32 s12, s30, 0x100080
	global_load_lds_dwordx4 v[0:1], off
	v_lshl_add_u64 v[0:1], v[2:3], 0, s[10:11]
	s_mov_b32 m0, s57
	s_addc_u32 s13, s31, 0
	global_load_lds_dwordx4 v[0:1], off
	s_add_i32 m0, s49, 0x1c000
	v_lshl_add_u64 v[0:1], s[12:13], 0, v[138:139]
	global_load_lds_dwordx4 v[0:1], off
	v_lshl_add_u64 v[0:1], s[12:13], 0, v[142:143]
	s_add_i32 m0, s49, 0x1e000
	v_bfe_u32 v159, v5, 4, 2
	global_load_lds_dwordx4 v[0:1], off
	v_and_b32_e32 v158, 15, v5
	v_lshlrev_b32_e32 v0, 4, v159
	v_lshlrev_b32_e32 v1, 2, v5
	v_lshl_or_b32 v0, v158, 6, v0
	v_and_b32_e32 v1, 32, v1
	v_bitop3_b32 v8, v0, s15, v1 bitop3:0xde
	v_bitop3_b32 v160, v0, s17, v1 bitop3:0xde
	v_add_u32_e32 v160, 0x10000, v160
	v_lshlrev_b32_e32 v0, 2, v172
	v_ashrrev_i32_e32 v1, 31, v0
	v_lshl_add_u64 v[2:3], v[0:1], 2, s[96:97]
	v_lshlrev_b32_e32 v1, 16, v10
	s_mov_b64 s[20:21], 0xc0000
	v_and_b32_e32 v1, 0xfffe0000, v1
	v_lshl_add_u64 v[144:145], v[2:3], 0, s[20:21]
	v_lshl_add_u32 v1, v11, 13, v1
	v_and_b32_e32 v2, 1, v10
	v_lshl_or_b32 v1, v2, 6, v1
	v_lshl_add_u32 v146, v12, 1, v1
	v_lshlrev_b32_e32 v1, 16, v13
	v_and_b32_e32 v1, 0xfffe0000, v1
	s_cmpk_lt_u32 s14, 0x100
	v_lshl_add_u32 v1, v14, 13, v1
	v_and_b32_e32 v2, 1, v13
	s_waitcnt vmcnt(6)
	s_cselect_b64 s[14:15], -1, 0
	s_cmp_eq_u32 s16, 0
	v_and_b32_e32 v0, 0x7c, v0
	v_lshl_or_b32 v1, v2, 6, v1
	v_mov_b32_e32 v5, v4
	s_cselect_b64 s[16:17], -1, 0
	s_add_u32 s20, s96, 0x80000
	v_lshl_add_u32 v148, v15, 1, v1
	v_mov_b32_e32 v6, v4
	v_mov_b32_e32 v7, v4
	v_lshlrev_b32_e32 v150, 2, v0
	v_mov_b64_e32 v[0:1], v[4:5]
	s_mov_b32 s13, 0
	s_addc_u32 s21, s97, 0
	v_lshlrev_b32_e32 v161, 3, v172
	v_mov_b32_e32 v147, v4
	v_mov_b32_e32 v149, v4
	v_mov_b32_e32 v174, s22
	v_mov_b32_e32 v162, s47
	s_movk_i32 s58, 0x1000
	s_add_i32 s59, 0, 0x10000
	s_add_i32 s60, 0, 0x14000
	v_add_u32_e32 v163, 0, v8
	s_movk_i32 s61, 0x6200
	s_movk_i32 s62, 0x98
	s_mov_b32 s63, 0xc400
	v_mov_b64_e32 v[2:3], v[6:7]
	s_mov_b32 s64, 0
	s_barrier
	s_waitcnt vmcnt(0)

.LBB0_236:
	s_add_i32 s12, s75, 2
	s_add_u32 s30, s28, 0xfff00080
	s_addc_u32 s31, s29, -1
	s_cmp_eq_u32 s72, s75
	s_cselect_b32 s35, s68, s31
	s_cselect_b32 s34, s69, s30
	s_cselect_b32 s31, s70, s74
	s_cselect_b32 s30, s71, s73
	s_cmpk_lt_i32 s3, 0x56
	s_cselect_b32 s36, s58, 0x2b00
	s_mov_b32 s37, 0xac00
	s_cselect_b32 s75, s37, 0x4000
	s_sub_i32 s36, s36, s33
	v_min3_i32 v5, s36, v174, 2
	v_sub_u32_e32 v174, v174, v5
	v_readfirstlane_b32 s78, v5
	s_max_i32 s36, s78, 0
	s_add_i32 s36, s33, s36
	s_add_i32 s76, s36, -1
	s_min_i32 s36, s33, s76
	s_mul_hi_i32 s37, s75, s36
	s_mul_i32 s36, s75, s36
	s_add_u32 s36, s38, s36
	s_addc_u32 s37, s39, s37
	s_mul_hi_i32 s77, s75, s76
	s_mul_i32 s75, s75, s76
	s_add_u32 s76, s38, s75
	global_load_dwordx4 v[152:155], v173, s[36:37] nt
	s_addc_u32 s77, s39, s77
	global_load_dwordx4 v[164:167], v173, s[76:77] nt
	s_add_i32 s33, s78, s33
	ds_read_b128 v[168:171], v160
	ds_read_b128 v[176:179], v160 offset:1024
	ds_read_b128 v[180:183], v160 offset:2048
	ds_read_b128 v[184:187], v160 offset:3072
	ds_read_b128 v[188:191], v160 offset:16384
	ds_read_b128 v[192:195], v160 offset:17408
	ds_read_b128 v[196:199], v160 offset:18432
	ds_read_b128 v[200:203], v160 offset:19456
	s_add_i32 m0, s49, 0xc000
	ds_read_b128 v[204:207], v163
	ds_read_b128 v[208:211], v163 offset:1024
	ds_read_b128 v[212:215], v163 offset:2048
	ds_read_b128 v[216:219], v163 offset:3072
	ds_read_b128 v[220:223], v163 offset:4096
	ds_read_b128 v[224:227], v163 offset:5120
	ds_read_b128 v[228:231], v163 offset:6144
	global_load_lds_dwordx4 v146, s[28:29]
	s_add_i32 m0, s49, 0xe000
	ds_read_b128 v[236:239], v163 offset:7168
	global_load_lds_dwordx4 v148, s[28:29]
	s_waitcnt vmcnt(10)
	s_waitcnt lgkmcnt(0)
	s_barrier
	s_setprio 1
	s_waitcnt lgkmcnt(0)
	v_mfma_f32_16x16x32_bf16 v[132:135], v[168:171], v[204:207], v[132:135]
	v_mfma_f32_16x16x32_bf16 v[128:131], v[180:183], v[204:207], v[128:131]
	v_mfma_f32_16x16x32_bf16 v[116:119], v[168:171], v[212:215], v[116:119]
	v_mfma_f32_16x16x32_bf16 v[112:115], v[180:183], v[212:215], v[112:115]
	v_mfma_f32_16x16x32_bf16 v[100:103], v[168:171], v[220:223], v[100:103]
	v_mfma_f32_16x16x32_bf16 v[96:99], v[180:183], v[220:223], v[96:99]
	v_mfma_f32_16x16x32_bf16 v[84:87], v[168:171], v[228:231], v[84:87]
	v_mfma_f32_16x16x32_bf16 v[80:83], v[180:183], v[228:231], v[80:83]
	v_mfma_f32_16x16x32_bf16 v[132:135], v[176:179], v[208:211], v[132:135]
	v_mfma_f32_16x16x32_bf16 v[128:131], v[184:187], v[208:211], v[128:131]
	v_mfma_f32_16x16x32_bf16 v[116:119], v[176:179], v[216:219], v[116:119]
	v_mfma_f32_16x16x32_bf16 v[112:115], v[184:187], v[216:219], v[112:115]
	v_mfma_f32_16x16x32_bf16 v[100:103], v[176:179], v[224:227], v[100:103]
	v_mfma_f32_16x16x32_bf16 v[96:99], v[184:187], v[224:227], v[96:99]
	v_mfma_f32_16x16x32_bf16 v[84:87], v[176:179], v[236:239], v[84:87]
	v_mfma_f32_16x16x32_bf16 v[80:83], v[184:187], v[236:239], v[80:83]
	s_setprio 0
	s_setprio 1
	v_mfma_f32_16x16x32_bf16 v[124:127], v[188:191], v[204:207], v[124:127]
	v_mfma_f32_16x16x32_bf16 v[120:123], v[196:199], v[204:207], v[120:123]
	v_mfma_f32_16x16x32_bf16 v[108:111], v[188:191], v[212:215], v[108:111]
	v_mfma_f32_16x16x32_bf16 v[104:107], v[196:199], v[212:215], v[104:107]
	v_mfma_f32_16x16x32_bf16 v[92:95], v[188:191], v[220:223], v[92:95]
	v_mfma_f32_16x16x32_bf16 v[88:91], v[196:199], v[220:223], v[88:91]
	v_mfma_f32_16x16x32_bf16 v[76:79], v[188:191], v[228:231], v[76:79]
	v_mfma_f32_16x16x32_bf16 v[72:75], v[196:199], v[228:231], v[72:75]
	v_mfma_f32_16x16x32_bf16 v[124:127], v[192:195], v[208:211], v[124:127]
	v_mfma_f32_16x16x32_bf16 v[120:123], v[200:203], v[208:211], v[120:123]
	v_mfma_f32_16x16x32_bf16 v[108:111], v[192:195], v[216:219], v[108:111]
	v_mfma_f32_16x16x32_bf16 v[104:107], v[200:203], v[216:219], v[104:107]
	v_mfma_f32_16x16x32_bf16 v[92:95], v[192:195], v[224:227], v[92:95]
	v_mfma_f32_16x16x32_bf16 v[88:91], v[200:203], v[224:227], v[88:91]
	v_mfma_f32_16x16x32_bf16 v[76:79], v[192:195], v[236:239], v[76:79]
	v_mfma_f32_16x16x32_bf16 v[72:75], v[200:203], v[236:239], v[72:75]
	s_setprio 0
	s_barrier
	s_add_i32 s36, s59, s48
	s_mov_b32 m0, s36
	ds_read_b128 v[204:207], v163 offset:16384
	ds_read_b128 v[208:211], v163 offset:17408
	ds_read_b128 v[212:215], v163 offset:18432
	ds_read_b128 v[216:219], v163 offset:19456
	global_load_lds_dwordx4 v138, s[30:31]
	s_add_i32 m0, s36, 0x2000
	s_add_u32 s36, s30, 0x100000
	s_addc_u32 s37, s31, 0
	s_add_i32 s75, s60, s48
	global_load_lds_dwordx4 v142, s[30:31]
	s_mov_b32 m0, s75
	ds_read_b128 v[236:239], v163 offset:23552
	global_load_lds_dwordx4 v138, s[36:37]
	s_add_i32 m0, s75, 0x2000
	ds_read_b128 v[228:231], v163 offset:22528
	global_load_lds_dwordx4 v142, s[36:37]
	s_mov_b32 m0, s49
	ds_read_b128 v[224:227], v163 offset:21504
	global_load_lds_dwordx4 v136, s[34:35]
	s_mov_b32 m0, s50
	ds_read_b128 v[220:223], v163 offset:20480
	global_load_lds_dwordx4 v140, s[34:35]
	s_waitcnt vmcnt(10)
	s_waitcnt lgkmcnt(0)
	s_barrier
	s_setprio 1
	s_waitcnt lgkmcnt(0)
	v_mfma_f32_16x16x32_bf16 v[68:71], v[168:171], v[204:207], v[68:71]
	v_mfma_f32_16x16x32_bf16 v[64:67], v[180:183], v[204:207], v[64:67]
	v_mfma_f32_16x16x32_bf16 v[52:55], v[168:171], v[212:215], v[52:55]
	v_mfma_f32_16x16x32_bf16 v[48:51], v[180:183], v[212:215], v[48:51]
	v_mfma_f32_16x16x32_bf16 v[36:39], v[168:171], v[220:223], v[36:39]
	v_mfma_f32_16x16x32_bf16 v[32:35], v[180:183], v[220:223], v[32:35]
	v_mfma_f32_16x16x32_bf16 v[20:23], v[168:171], v[228:231], v[20:23]
	v_mfma_f32_16x16x32_bf16 v[16:19], v[180:183], v[228:231], v[16:19]
	v_mfma_f32_16x16x32_bf16 v[68:71], v[176:179], v[208:211], v[68:71]
	v_mfma_f32_16x16x32_bf16 v[64:67], v[184:187], v[208:211], v[64:67]
	v_mfma_f32_16x16x32_bf16 v[52:55], v[176:179], v[216:219], v[52:55]
	v_mfma_f32_16x16x32_bf16 v[48:51], v[184:187], v[216:219], v[48:51]
	v_mfma_f32_16x16x32_bf16 v[36:39], v[176:179], v[224:227], v[36:39]
	v_mfma_f32_16x16x32_bf16 v[32:35], v[184:187], v[224:227], v[32:35]
	v_mfma_f32_16x16x32_bf16 v[20:23], v[176:179], v[236:239], v[20:23]
	v_mfma_f32_16x16x32_bf16 v[16:19], v[184:187], v[236:239], v[16:19]
	s_setprio 0
	s_setprio 1
	v_mfma_f32_16x16x32_bf16 v[60:63], v[188:191], v[204:207], v[60:63]
	v_mfma_f32_16x16x32_bf16 v[56:59], v[196:199], v[204:207], v[56:59]
	v_mfma_f32_16x16x32_bf16 v[44:47], v[188:191], v[212:215], v[44:47]
	v_mfma_f32_16x16x32_bf16 v[40:43], v[196:199], v[212:215], v[40:43]
	v_mfma_f32_16x16x32_bf16 v[28:31], v[188:191], v[220:223], v[28:31]
	v_mfma_f32_16x16x32_bf16 v[24:27], v[196:199], v[220:223], v[24:27]
	v_mfma_f32_16x16x32_bf16 v[12:15], v[188:191], v[228:231], v[12:15]
	v_mfma_f32_16x16x32_bf16 v[6:9], v[196:199], v[228:231], v[8:11]
	v_mfma_f32_16x16x32_bf16 v[60:63], v[192:195], v[208:211], v[60:63]
	v_mfma_f32_16x16x32_bf16 v[56:59], v[200:203], v[208:211], v[56:59]
	v_mfma_f32_16x16x32_bf16 v[44:47], v[192:195], v[216:219], v[44:47]
	v_mfma_f32_16x16x32_bf16 v[40:43], v[200:203], v[216:219], v[40:43]
	v_mfma_f32_16x16x32_bf16 v[28:31], v[192:195], v[224:227], v[28:31]
	v_mfma_f32_16x16x32_bf16 v[24:27], v[200:203], v[224:227], v[24:27]
	v_mfma_f32_16x16x32_bf16 v[12:15], v[192:195], v[236:239], v[12:15]
	v_mfma_f32_16x16x32_bf16 v[6:9], v[200:203], v[236:239], v[6:9]
	s_setprio 0
	s_barrier
	s_add_i32 s36, 0, 0x18000
	s_add_i32 s37, 0, 0x1c000
	ds_read_b128 v[168:171], v160 offset:32768
	ds_read_b128 v[176:179], v160 offset:33792
	ds_read_b128 v[180:183], v160 offset:34816
	ds_read_b128 v[184:187], v160 offset:35840
	ds_read_b128 v[188:191], v160 offset:49152
	ds_read_b128 v[192:195], v160 offset:50176
	ds_read_b128 v[196:199], v160 offset:51200
	ds_read_b128 v[200:203], v160 offset:52224
	s_add_u32 s34, s34, 0x100000
	s_addc_u32 s35, s35, 0
	s_mov_b32 m0, s51
	ds_read_b128 v[204:207], v163 offset:32768
	ds_read_b128 v[208:211], v163 offset:33792
	ds_read_b128 v[212:215], v163 offset:34816
	ds_read_b128 v[216:219], v163 offset:35840
	ds_read_b128 v[220:223], v163 offset:36864
	ds_read_b128 v[224:227], v163 offset:37888
	ds_read_b128 v[228:231], v163 offset:38912
	global_load_lds_dwordx4 v136, s[34:35]
	s_mov_b32 m0, s52
	ds_read_b128 v[236:239], v163 offset:39936
	global_load_lds_dwordx4 v140, s[34:35]
	s_waitcnt vmcnt(8)
	s_waitcnt lgkmcnt(0)
	s_barrier
	s_setprio 1
	s_waitcnt lgkmcnt(0)
	v_mfma_f32_16x16x32_bf16 v[132:135], v[168:171], v[204:207], v[132:135]
	v_mfma_f32_16x16x32_bf16 v[128:131], v[180:183], v[204:207], v[128:131]
	v_mfma_f32_16x16x32_bf16 v[116:119], v[168:171], v[212:215], v[116:119]
	v_mfma_f32_16x16x32_bf16 v[112:115], v[180:183], v[212:215], v[112:115]
	v_mfma_f32_16x16x32_bf16 v[100:103], v[168:171], v[220:223], v[100:103]
	v_max3_f32 v0, v0, |v152|, |v164|
	v_mfma_f32_16x16x32_bf16 v[96:99], v[180:183], v[220:223], v[96:99]
	v_max3_f32 v1, v1, |v153|, |v165|
	v_mfma_f32_16x16x32_bf16 v[84:87], v[168:171], v[228:231], v[84:87]
	v_max3_f32 v2, v2, |v154|, |v166|
	v_mfma_f32_16x16x32_bf16 v[80:83], v[180:183], v[228:231], v[80:83]
	v_max3_f32 v3, v3, |v155|, |v167|
	v_mfma_f32_16x16x32_bf16 v[132:135], v[176:179], v[208:211], v[132:135]
	v_mfma_f32_16x16x32_bf16 v[128:131], v[184:187], v[208:211], v[128:131]
	v_mfma_f32_16x16x32_bf16 v[116:119], v[176:179], v[216:219], v[116:119]
	v_mfma_f32_16x16x32_bf16 v[112:115], v[184:187], v[216:219], v[112:115]
	v_mfma_f32_16x16x32_bf16 v[100:103], v[176:179], v[224:227], v[100:103]
	v_mfma_f32_16x16x32_bf16 v[96:99], v[184:187], v[224:227], v[96:99]
	v_mfma_f32_16x16x32_bf16 v[84:87], v[176:179], v[236:239], v[84:87]
	v_mfma_f32_16x16x32_bf16 v[80:83], v[184:187], v[236:239], v[80:83]
	s_setprio 0
	s_setprio 1
	v_mfma_f32_16x16x32_bf16 v[124:127], v[188:191], v[204:207], v[124:127]
	v_mfma_f32_16x16x32_bf16 v[120:123], v[196:199], v[204:207], v[120:123]
	v_mfma_f32_16x16x32_bf16 v[108:111], v[188:191], v[212:215], v[108:111]
	v_mfma_f32_16x16x32_bf16 v[104:107], v[196:199], v[212:215], v[104:107]
	v_mfma_f32_16x16x32_bf16 v[92:95], v[188:191], v[220:223], v[92:95]
	v_mfma_f32_16x16x32_bf16 v[88:91], v[196:199], v[220:223], v[88:91]
	v_mfma_f32_16x16x32_bf16 v[76:79], v[188:191], v[228:231], v[76:79]
	v_mfma_f32_16x16x32_bf16 v[72:75], v[196:199], v[228:231], v[72:75]
	v_mfma_f32_16x16x32_bf16 v[124:127], v[192:195], v[208:211], v[124:127]
	v_mfma_f32_16x16x32_bf16 v[120:123], v[200:203], v[208:211], v[120:123]
	v_mfma_f32_16x16x32_bf16 v[108:111], v[192:195], v[216:219], v[108:111]
	v_mfma_f32_16x16x32_bf16 v[104:107], v[200:203], v[216:219], v[104:107]
	v_mfma_f32_16x16x32_bf16 v[92:95], v[192:195], v[224:227], v[92:95]
	v_mfma_f32_16x16x32_bf16 v[88:91], v[200:203], v[224:227], v[88:91]
	v_mfma_f32_16x16x32_bf16 v[76:79], v[192:195], v[236:239], v[76:79]
	v_mfma_f32_16x16x32_bf16 v[72:75], v[200:203], v[236:239], v[72:75]
	s_setprio 0
	s_barrier
	s_add_u32 s98, s30, s10
	s_addc_u32 s99, s31, s11
	s_add_u32 s100, s34, s10
	s_addc_u32 s101, s35, s11
	s_sub_u32 s100, s100, 0x100000
	s_subb_u32 s101, s101, 0
	s_add_i32 s34, s36, s48
	s_mov_b32 m0, s34
	ds_read_b128 v[152:155], v163 offset:49152
	ds_read_b128 v[164:167], v163 offset:50176
	ds_read_b128 v[204:207], v163 offset:51200
	ds_read_b128 v[208:211], v163 offset:52224
	global_load_lds_dwordx4 v138, s[98:99]
	s_add_i32 m0, s34, 0x2000
	s_add_u32 s30, s30, 0x100080
	s_addc_u32 s31, s31, 0
	s_add_i32 s34, s37, s48
	global_load_lds_dwordx4 v142, s[98:99]
	s_mov_b32 m0, s34
	ds_read_b128 v[224:227], v163 offset:56320
	global_load_lds_dwordx4 v138, s[30:31]
	s_add_i32 m0, s34, 0x2000
	ds_read_b128 v[220:223], v163 offset:55296
	global_load_lds_dwordx4 v142, s[30:31]
	s_mov_b32 m0, s56
	ds_read_b128 v[216:219], v163 offset:54272
	global_load_lds_dwordx4 v136, s[100:101]
	s_mov_b32 m0, s57
	ds_read_b128 v[212:215], v163 offset:53248
	global_load_lds_dwordx4 v140, s[100:101]
	s_waitcnt vmcnt(8)
	s_waitcnt lgkmcnt(0)
	s_barrier
	s_setprio 1
	s_waitcnt lgkmcnt(0)
	v_mfma_f32_16x16x32_bf16 v[68:71], v[168:171], v[152:155], v[68:71]
	v_mfma_f32_16x16x32_bf16 v[64:67], v[180:183], v[152:155], v[64:67]
	v_mfma_f32_16x16x32_bf16 v[52:55], v[168:171], v[204:207], v[52:55]
	v_mfma_f32_16x16x32_bf16 v[48:51], v[180:183], v[204:207], v[48:51]
	v_mfma_f32_16x16x32_bf16 v[36:39], v[168:171], v[212:215], v[36:39]
	v_mfma_f32_16x16x32_bf16 v[32:35], v[180:183], v[212:215], v[32:35]
	v_mfma_f32_16x16x32_bf16 v[20:23], v[168:171], v[220:223], v[20:23]
	v_mfma_f32_16x16x32_bf16 v[16:19], v[180:183], v[220:223], v[16:19]
	v_mfma_f32_16x16x32_bf16 v[68:71], v[176:179], v[164:167], v[68:71]
	v_mfma_f32_16x16x32_bf16 v[64:67], v[184:187], v[164:167], v[64:67]
	v_mfma_f32_16x16x32_bf16 v[52:55], v[176:179], v[208:211], v[52:55]
	v_mfma_f32_16x16x32_bf16 v[48:51], v[184:187], v[208:211], v[48:51]
	v_mfma_f32_16x16x32_bf16 v[36:39], v[176:179], v[216:219], v[36:39]
	v_mfma_f32_16x16x32_bf16 v[32:35], v[184:187], v[216:219], v[32:35]
	v_mfma_f32_16x16x32_bf16 v[20:23], v[176:179], v[224:227], v[20:23]
	v_mfma_f32_16x16x32_bf16 v[16:19], v[184:187], v[224:227], v[16:19]
	s_setprio 0
	s_setprio 1
	v_mfma_f32_16x16x32_bf16 v[60:63], v[188:191], v[152:155], v[60:63]
	v_mfma_f32_16x16x32_bf16 v[56:59], v[196:199], v[152:155], v[56:59]
	v_mfma_f32_16x16x32_bf16 v[44:47], v[188:191], v[204:207], v[44:47]
	v_mfma_f32_16x16x32_bf16 v[40:43], v[196:199], v[204:207], v[40:43]
	v_mfma_f32_16x16x32_bf16 v[28:31], v[188:191], v[212:215], v[28:31]
	v_mfma_f32_16x16x32_bf16 v[24:27], v[196:199], v[212:215], v[24:27]
	v_mfma_f32_16x16x32_bf16 v[10:13], v[188:191], v[220:223], v[12:15]
	v_mfma_f32_16x16x32_bf16 v[6:9], v[196:199], v[220:223], v[6:9]
	v_mfma_f32_16x16x32_bf16 v[60:63], v[192:195], v[164:167], v[60:63]
	v_mfma_f32_16x16x32_bf16 v[56:59], v[200:203], v[164:167], v[56:59]
	v_mfma_f32_16x16x32_bf16 v[44:47], v[192:195], v[208:211], v[44:47]
	v_mfma_f32_16x16x32_bf16 v[40:43], v[200:203], v[208:211], v[40:43]
	v_mfma_f32_16x16x32_bf16 v[28:31], v[192:195], v[216:219], v[28:31]
	v_mfma_f32_16x16x32_bf16 v[24:27], v[200:203], v[216:219], v[24:27]
	v_mfma_f32_16x16x32_bf16 v[12:15], v[192:195], v[224:227], v[10:13]
	v_mfma_f32_16x16x32_bf16 v[8:11], v[200:203], v[224:227], v[6:9]
	s_setprio 0
	s_barrier
	s_add_u32 s28, s28, 0x100
	s_addc_u32 s29, s29, 0
	s_add_u32 s73, s73, 0x100
	s_addc_u32 s74, s74, 0
	s_cmp_ge_i32 s12, s67
	s_cbranch_scc0 .LBB0_221
	s_and_b64 vcc, exec, s[14:15]
	s_cbranch_vccz .LBB0_239

.LBB0_296:
	s_add_u32 s50, s96, 0x37907400
	s_addc_u32 s51, s97, 0
	s_add_u32 s12, s96, 0xc8000
	s_addc_u32 s13, s97, 0
	s_lshl_b32 s14, s14, 5
	s_and_b32 s53, s14, 0x60
	s_mov_b64 s[14:15], 0x80
	s_add_i32 m0, s46, 0x18000
	v_lshl_add_u64 v[12:13], v[12:13], 0, s[14:15]
	s_lshl_b32 s52, s8, 6
	s_lshl_b32 s8, s8, 13
	s_lshl_b32 s17, s53, 7
	s_waitcnt vmcnt(2)
	s_barrier
	global_load_lds_dwordx4 v[12:13], off
	v_lshl_add_u64 v[10:11], v[10:11], 0, s[14:15]
	s_add_i32 m0, s46, 0x1a000
	s_add_i32 s54, s46, 0x8000
	s_add_i32 s55, s46, 0xa000
	global_load_lds_dwordx4 v[10:11], off
	v_lshl_add_u64 v[6:7], v[6:7], 0, s[14:15]
	s_mov_b32 m0, s54
	s_add_u32 s20, s34, 0x80080
	global_load_lds_dwordx4 v[6:7], off
	v_lshl_add_u64 v[6:7], v[8:9], 0, s[14:15]
	s_mov_b32 m0, s55
	s_addc_u32 s21, s35, 0
	global_load_lds_dwordx4 v[6:7], off
	s_add_i32 m0, s46, 0x1c000
	v_lshl_add_u64 v[6:7], s[20:21], 0, v[138:139]
	global_load_lds_dwordx4 v[6:7], off
	v_lshl_add_u64 v[6:7], s[20:21], 0, v[142:143]
	s_add_i32 m0, s46, 0x1e000
	v_bfe_u32 v176, v5, 4, 2
	global_load_lds_dwordx4 v[6:7], off
	v_and_b32_e32 v175, 15, v5
	v_lshlrev_b32_e32 v6, 4, v176
	v_lshlrev_b32_e32 v5, 2, v5
	v_lshl_or_b32 v6, v175, 6, v6
	v_and_b32_e32 v5, 32, v5
	v_bitop3_b32 v10, v6, s8, v5 bitop3:0xde
	v_bitop3_b32 v177, v6, s17, v5 bitop3:0xde
	v_add_u32_e32 v177, 0x10000, v177
	v_lshlrev_b32_e32 v6, 2, v172
	v_lshlrev_b32_e32 v5, 15, v14
	v_ashrrev_i32_e32 v7, 31, v6
	v_and_b32_e32 v5, 0xffff0000, v5
	v_lshl_add_u64 v[8:9], v[6:7], 2, s[96:97]
	v_lshl_add_u32 v5, v15, 12, v5
	v_and_b32_e32 v7, 1, v14
	v_lshl_or_b32 v5, v7, 6, v5
	v_lshl_add_u32 v146, v16, 1, v5
	v_lshlrev_b32_e32 v5, 15, v17
	v_and_b32_e32 v5, 0xffff0000, v5
	s_waitcnt vmcnt(6)
	s_cmpk_lt_u32 s16, 0x100
	s_mov_b64 s[20:21], 0xc0000
	v_lshl_add_u32 v5, v18, 12, v5
	v_and_b32_e32 v7, 1, v17
	s_cselect_b64 s[16:17], -1, 0
	v_lshl_add_u64 v[144:145], v[8:9], 0, s[20:21]
	s_add_u32 s20, s96, 0x80000
	v_and_b32_e32 v6, 0x7c, v6
	v_lshl_or_b32 v5, v7, 6, v5
	s_addc_u32 s21, s97, 0
	v_lshlrev_b32_e32 v178, 3, v172
	v_mov_b32_e32 v147, v4
	v_lshl_add_u32 v148, v19, 1, v5
	v_mov_b32_e32 v149, v4
	v_mov_b32_e32 v179, s44
	s_movk_i32 s56, 0x1000
	v_lshlrev_b32_e32 v150, 2, v6
	s_add_i32 s57, 0, 0x10000
	s_add_i32 s58, 0, 0x14000
	v_add_u32_e32 v180, 0, v10
	s_mov_b32 s22, 0x3c010204
	s_movk_i32 s59, 0x98
	s_mov_b32 s60, 0xc400
	s_movk_i32 s61, 0x6200
	s_mov_b32 s62, 0
	s_barrier

.Lp1i_body:
	s_add_i32 s8, s74, 2
	s_add_u32 s34, s30, 0xfff80080
	s_addc_u32 s35, s31, -1
	s_cmp_eq_u32 s71, s74
	s_cselect_b32 s37, s67, s35
	s_cselect_b32 s36, s68, s34
	s_cselect_b32 s35, s69, s73
	s_cselect_b32 s34, s70, s72
	ds_read_b128 v[160:163], v177
	ds_read_b128 v[164:167], v177 offset:1024
	ds_read_b128 v[168:171], v177 offset:2048
	ds_read_b128 v[182:185], v177 offset:3072
	ds_read_b128 v[186:189], v177 offset:16384
	ds_read_b128 v[190:193], v177 offset:17408
	ds_read_b128 v[194:197], v177 offset:18432
	ds_read_b128 v[198:201], v177 offset:19456
	s_add_i32 m0, s46, 0xc000
	ds_read_b128 v[202:205], v180
	ds_read_b128 v[206:209], v180 offset:1024
	ds_read_b128 v[210:213], v180 offset:2048
	ds_read_b128 v[214:217], v180 offset:3072
	ds_read_b128 v[218:221], v180 offset:4096
	ds_read_b128 v[222:225], v180 offset:5120
	ds_read_b128 v[226:229], v180 offset:6144
	global_load_lds_dwordx4 v146, s[30:31]
	s_add_i32 m0, s46, 0xe000
	ds_read_b128 v[230:233], v180 offset:7168
	global_load_lds_dwordx4 v148, s[30:31]
	s_waitcnt vmcnt(8)
	s_waitcnt lgkmcnt(0)
	s_barrier
	s_setprio 1
	s_waitcnt lgkmcnt(0)
	v_mfma_i32_16x16x64_i8 v[132:135], v[160:163], v[202:205], v[132:135]
	v_mfma_i32_16x16x64_i8 v[128:131], v[168:171], v[202:205], v[128:131]
	v_mfma_i32_16x16x64_i8 v[124:127], v[160:163], v[210:213], v[124:127]
	v_mfma_i32_16x16x64_i8 v[120:123], v[168:171], v[210:213], v[120:123]
	v_mfma_i32_16x16x64_i8 v[112:115], v[160:163], v[218:221], v[112:115]
	v_mfma_i32_16x16x64_i8 v[104:107], v[168:171], v[218:221], v[104:107]
	v_mfma_i32_16x16x64_i8 v[96:99], v[160:163], v[226:229], v[96:99]
	v_mfma_i32_16x16x64_i8 v[88:91], v[168:171], v[226:229], v[88:91]
	v_mfma_i32_16x16x64_i8 v[132:135], v[164:167], v[206:209], v[132:135]
	v_mfma_i32_16x16x64_i8 v[128:131], v[182:185], v[206:209], v[128:131]
	v_mfma_i32_16x16x64_i8 v[124:127], v[164:167], v[214:217], v[124:127]
	v_mfma_i32_16x16x64_i8 v[120:123], v[182:185], v[214:217], v[120:123]
	v_mfma_i32_16x16x64_i8 v[112:115], v[164:167], v[222:225], v[112:115]
	v_mfma_i32_16x16x64_i8 v[104:107], v[182:185], v[222:225], v[104:107]
	v_mfma_i32_16x16x64_i8 v[96:99], v[164:167], v[230:233], v[96:99]
	v_mfma_i32_16x16x64_i8 v[88:91], v[182:185], v[230:233], v[88:91]
	s_setprio 0
	s_setprio 1
	v_mfma_i32_16x16x64_i8 v[116:119], v[186:189], v[202:205], v[116:119]
	v_mfma_i32_16x16x64_i8 v[108:111], v[194:197], v[202:205], v[108:111]
	v_mfma_i32_16x16x64_i8 v[100:103], v[186:189], v[210:213], v[100:103]
	v_mfma_i32_16x16x64_i8 v[92:95], v[194:197], v[210:213], v[92:95]
	v_mfma_i32_16x16x64_i8 v[84:87], v[186:189], v[218:221], v[84:87]
	v_mfma_i32_16x16x64_i8 v[80:83], v[194:197], v[218:221], v[80:83]
	v_mfma_i32_16x16x64_i8 v[76:79], v[186:189], v[226:229], v[76:79]
	v_mfma_i32_16x16x64_i8 v[72:75], v[194:197], v[226:229], v[72:75]
	v_mfma_i32_16x16x64_i8 v[116:119], v[190:193], v[206:209], v[116:119]
	v_mfma_i32_16x16x64_i8 v[108:111], v[198:201], v[206:209], v[108:111]
	v_mfma_i32_16x16x64_i8 v[100:103], v[190:193], v[214:217], v[100:103]
	v_mfma_i32_16x16x64_i8 v[92:95], v[198:201], v[214:217], v[92:95]
	v_mfma_i32_16x16x64_i8 v[84:87], v[190:193], v[222:225], v[84:87]
	v_mfma_i32_16x16x64_i8 v[80:83], v[198:201], v[222:225], v[80:83]
	v_mfma_i32_16x16x64_i8 v[76:79], v[190:193], v[230:233], v[76:79]
	v_mfma_i32_16x16x64_i8 v[72:75], v[198:201], v[230:233], v[72:75]
	s_setprio 0
	s_barrier
	s_add_i32 s74, s57, s45
	s_mov_b32 m0, s74
	ds_read_b128 v[202:205], v180 offset:16384
	ds_read_b128 v[206:209], v180 offset:17408
	ds_read_b128 v[210:213], v180 offset:18432
	ds_read_b128 v[214:217], v180 offset:19456
	global_load_lds_dwordx4 v138, s[34:35]
	s_add_i32 m0, s74, 0x2000
	s_add_u32 s74, s34, 0x80000
	s_addc_u32 s75, s35, 0
	s_add_i32 s76, s58, s45
	global_load_lds_dwordx4 v142, s[34:35]
	s_mov_b32 m0, s76
	ds_read_b128 v[230:233], v180 offset:23552
	global_load_lds_dwordx4 v138, s[74:75]
	s_add_i32 m0, s76, 0x2000
	ds_read_b128 v[226:229], v180 offset:22528
	global_load_lds_dwordx4 v142, s[74:75]
	s_mov_b32 m0, s46
	ds_read_b128 v[222:225], v180 offset:21504
	global_load_lds_dwordx4 v136, s[36:37]
	s_mov_b32 m0, s47
	ds_read_b128 v[218:221], v180 offset:20480
	global_load_lds_dwordx4 v140, s[36:37]
	s_waitcnt vmcnt(8)
	s_waitcnt lgkmcnt(0)
	s_barrier
	s_setprio 1
	s_waitcnt lgkmcnt(0)
	v_mfma_i32_16x16x64_i8 v[68:71], v[160:163], v[202:205], v[68:71]
	v_mfma_i32_16x16x64_i8 v[64:67], v[168:171], v[202:205], v[64:67]
	v_mfma_i32_16x16x64_i8 v[60:63], v[160:163], v[210:213], v[60:63]
	v_mfma_i32_16x16x64_i8 v[56:59], v[168:171], v[210:213], v[56:59]
	v_mfma_i32_16x16x64_i8 v[48:51], v[160:163], v[218:221], v[48:51]
	v_mfma_i32_16x16x64_i8 v[40:43], v[168:171], v[218:221], v[40:43]
	v_mfma_i32_16x16x64_i8 v[32:35], v[160:163], v[226:229], v[32:35]
	v_mfma_i32_16x16x64_i8 v[24:27], v[168:171], v[226:229], v[24:27]
	v_mfma_i32_16x16x64_i8 v[68:71], v[164:167], v[206:209], v[68:71]
	v_mfma_i32_16x16x64_i8 v[64:67], v[182:185], v[206:209], v[64:67]
	v_mfma_i32_16x16x64_i8 v[60:63], v[164:167], v[214:217], v[60:63]
	v_mfma_i32_16x16x64_i8 v[56:59], v[182:185], v[214:217], v[56:59]
	v_mfma_i32_16x16x64_i8 v[48:51], v[164:167], v[222:225], v[48:51]
	v_mfma_i32_16x16x64_i8 v[40:43], v[182:185], v[222:225], v[40:43]
	v_mfma_i32_16x16x64_i8 v[32:35], v[164:167], v[230:233], v[32:35]
	v_mfma_i32_16x16x64_i8 v[24:27], v[182:185], v[230:233], v[24:27]
	s_setprio 0
	s_setprio 1
	v_mfma_i32_16x16x64_i8 v[52:55], v[186:189], v[202:205], v[52:55]
	v_mfma_i32_16x16x64_i8 v[44:47], v[194:197], v[202:205], v[44:47]
	v_mfma_i32_16x16x64_i8 v[36:39], v[186:189], v[210:213], v[36:39]
	v_mfma_i32_16x16x64_i8 v[28:31], v[194:197], v[210:213], v[28:31]
	v_mfma_i32_16x16x64_i8 v[20:23], v[186:189], v[218:221], v[20:23]
	v_mfma_i32_16x16x64_i8 v[16:19], v[194:197], v[218:221], v[16:19]
	v_mfma_i32_16x16x64_i8 v[12:15], v[186:189], v[226:229], v[12:15]
	v_mfma_i32_16x16x64_i8 v[6:9], v[194:197], v[226:229], v[8:11]
	v_mfma_i32_16x16x64_i8 v[52:55], v[190:193], v[206:209], v[52:55]
	v_mfma_i32_16x16x64_i8 v[44:47], v[198:201], v[206:209], v[44:47]
	v_mfma_i32_16x16x64_i8 v[36:39], v[190:193], v[214:217], v[36:39]
	v_mfma_i32_16x16x64_i8 v[28:31], v[198:201], v[214:217], v[28:31]
	v_mfma_i32_16x16x64_i8 v[20:23], v[190:193], v[222:225], v[20:23]
	v_mfma_i32_16x16x64_i8 v[16:19], v[198:201], v[222:225], v[16:19]
	v_mfma_i32_16x16x64_i8 v[12:15], v[190:193], v[230:233], v[12:15]
	v_mfma_i32_16x16x64_i8 v[6:9], v[198:201], v[230:233], v[6:9]
	s_setprio 0
	s_barrier
	s_add_i32 s74, 0, 0x18000
	s_add_i32 s75, 0, 0x1c000
	ds_read_b128 v[160:163], v177 offset:32768
	ds_read_b128 v[164:167], v177 offset:33792
	ds_read_b128 v[168:171], v177 offset:34816
	ds_read_b128 v[182:185], v177 offset:35840
	ds_read_b128 v[186:189], v177 offset:49152
	ds_read_b128 v[190:193], v177 offset:50176
	ds_read_b128 v[194:197], v177 offset:51200
	ds_read_b128 v[198:201], v177 offset:52224
	s_add_u32 s36, s36, 0x80000
	s_addc_u32 s37, s37, 0
	s_mov_b32 m0, s48
	ds_read_b128 v[202:205], v180 offset:32768
	ds_read_b128 v[206:209], v180 offset:33792
	ds_read_b128 v[210:213], v180 offset:34816
	ds_read_b128 v[214:217], v180 offset:35840
	ds_read_b128 v[218:221], v180 offset:36864
	ds_read_b128 v[222:225], v180 offset:37888
	ds_read_b128 v[226:229], v180 offset:38912
	global_load_lds_dwordx4 v136, s[36:37]
	s_mov_b32 m0, s49
	ds_read_b128 v[230:233], v180 offset:39936
	global_load_lds_dwordx4 v140, s[36:37]
	s_waitcnt vmcnt(8)
	s_waitcnt lgkmcnt(0)
	s_barrier
	s_setprio 1
	s_waitcnt lgkmcnt(0)
	v_mfma_i32_16x16x64_i8 v[132:135], v[160:163], v[202:205], v[132:135]
	v_mfma_i32_16x16x64_i8 v[128:131], v[168:171], v[202:205], v[128:131]
	v_mfma_i32_16x16x64_i8 v[124:127], v[160:163], v[210:213], v[124:127]
	v_mfma_i32_16x16x64_i8 v[120:123], v[168:171], v[210:213], v[120:123]
	v_mfma_i32_16x16x64_i8 v[112:115], v[160:163], v[218:221], v[112:115]
	v_mfma_i32_16x16x64_i8 v[104:107], v[168:171], v[218:221], v[104:107]
	v_mfma_i32_16x16x64_i8 v[96:99], v[160:163], v[226:229], v[96:99]
	v_mfma_i32_16x16x64_i8 v[88:91], v[168:171], v[226:229], v[88:91]
	v_mfma_i32_16x16x64_i8 v[132:135], v[164:167], v[206:209], v[132:135]
	v_mfma_i32_16x16x64_i8 v[128:131], v[182:185], v[206:209], v[128:131]
	v_mfma_i32_16x16x64_i8 v[124:127], v[164:167], v[214:217], v[124:127]
	v_mfma_i32_16x16x64_i8 v[120:123], v[182:185], v[214:217], v[120:123]
	v_mfma_i32_16x16x64_i8 v[112:115], v[164:167], v[222:225], v[112:115]
	v_mfma_i32_16x16x64_i8 v[104:107], v[182:185], v[222:225], v[104:107]
	v_mfma_i32_16x16x64_i8 v[96:99], v[164:167], v[230:233], v[96:99]
	v_mfma_i32_16x16x64_i8 v[88:91], v[182:185], v[230:233], v[88:91]
	s_setprio 0
	s_setprio 1
	v_mfma_i32_16x16x64_i8 v[116:119], v[186:189], v[202:205], v[116:119]
	v_mfma_i32_16x16x64_i8 v[108:111], v[194:197], v[202:205], v[108:111]
	v_mfma_i32_16x16x64_i8 v[100:103], v[186:189], v[210:213], v[100:103]
	v_mfma_i32_16x16x64_i8 v[92:95], v[194:197], v[210:213], v[92:95]
	v_mfma_i32_16x16x64_i8 v[84:87], v[186:189], v[218:221], v[84:87]
	v_mfma_i32_16x16x64_i8 v[80:83], v[194:197], v[218:221], v[80:83]
	v_mfma_i32_16x16x64_i8 v[76:79], v[186:189], v[226:229], v[76:79]
	v_mfma_i32_16x16x64_i8 v[72:75], v[194:197], v[226:229], v[72:75]
	v_mfma_i32_16x16x64_i8 v[116:119], v[190:193], v[206:209], v[116:119]
	v_mfma_i32_16x16x64_i8 v[108:111], v[198:201], v[206:209], v[108:111]
	v_mfma_i32_16x16x64_i8 v[100:103], v[190:193], v[214:217], v[100:103]
	v_mfma_i32_16x16x64_i8 v[92:95], v[198:201], v[214:217], v[92:95]
	v_mfma_i32_16x16x64_i8 v[84:87], v[190:193], v[222:225], v[84:87]
	v_mfma_i32_16x16x64_i8 v[80:83], v[198:201], v[222:225], v[80:83]
	v_mfma_i32_16x16x64_i8 v[76:79], v[190:193], v[230:233], v[76:79]
	v_mfma_i32_16x16x64_i8 v[72:75], v[198:201], v[230:233], v[72:75]
	s_setprio 0
	s_barrier
	s_add_u32 s98, s34, s14
	s_addc_u32 s99, s35, s15
	s_add_u32 s100, s36, s14
	s_addc_u32 s101, s37, s15
	s_sub_u32 s100, s100, 0x80000
	s_subb_u32 s101, s101, 0
	s_add_i32 s36, s74, s45
	s_mov_b32 m0, s36
	ds_read_b128 v[152:155], v180 offset:49152
	ds_read_b128 v[156:159], v180 offset:50176
	ds_read_b128 v[202:205], v180 offset:51200
	ds_read_b128 v[206:209], v180 offset:52224
	global_load_lds_dwordx4 v138, s[98:99]
	s_add_i32 m0, s36, 0x2000
	s_add_u32 s34, s34, 0x80080
	s_addc_u32 s35, s35, 0
	s_add_i32 s36, s75, s45
	global_load_lds_dwordx4 v142, s[98:99]
	s_mov_b32 m0, s36
	ds_read_b128 v[222:225], v180 offset:56320
	global_load_lds_dwordx4 v138, s[34:35]
	s_add_i32 m0, s36, 0x2000
	ds_read_b128 v[218:221], v180 offset:55296
	global_load_lds_dwordx4 v142, s[34:35]
	s_mov_b32 m0, s54
	ds_read_b128 v[214:217], v180 offset:54272
	global_load_lds_dwordx4 v136, s[100:101]
	s_mov_b32 m0, s55
	ds_read_b128 v[210:213], v180 offset:53248
	global_load_lds_dwordx4 v140, s[100:101]
	s_waitcnt vmcnt(8)
	s_waitcnt lgkmcnt(0)
	s_barrier
	s_setprio 1
	s_waitcnt lgkmcnt(0)
	v_mfma_i32_16x16x64_i8 v[68:71], v[160:163], v[152:155], v[68:71]
	v_mfma_i32_16x16x64_i8 v[64:67], v[168:171], v[152:155], v[64:67]
	v_mfma_i32_16x16x64_i8 v[60:63], v[160:163], v[202:205], v[60:63]
	v_mfma_i32_16x16x64_i8 v[56:59], v[168:171], v[202:205], v[56:59]
	v_mfma_i32_16x16x64_i8 v[48:51], v[160:163], v[210:213], v[48:51]
	v_mfma_i32_16x16x64_i8 v[40:43], v[168:171], v[210:213], v[40:43]
	v_mfma_i32_16x16x64_i8 v[32:35], v[160:163], v[218:221], v[32:35]
	v_mfma_i32_16x16x64_i8 v[24:27], v[168:171], v[218:221], v[24:27]
	v_mfma_i32_16x16x64_i8 v[68:71], v[164:167], v[156:159], v[68:71]
	v_mfma_i32_16x16x64_i8 v[64:67], v[182:185], v[156:159], v[64:67]
	v_mfma_i32_16x16x64_i8 v[60:63], v[164:167], v[206:209], v[60:63]
	v_mfma_i32_16x16x64_i8 v[56:59], v[182:185], v[206:209], v[56:59]
	v_mfma_i32_16x16x64_i8 v[48:51], v[164:167], v[214:217], v[48:51]
	v_mfma_i32_16x16x64_i8 v[40:43], v[182:185], v[214:217], v[40:43]
	v_mfma_i32_16x16x64_i8 v[32:35], v[164:167], v[222:225], v[32:35]
	v_mfma_i32_16x16x64_i8 v[24:27], v[182:185], v[222:225], v[24:27]
	s_setprio 0
	s_setprio 1
	v_mfma_i32_16x16x64_i8 v[52:55], v[186:189], v[152:155], v[52:55]
	v_mfma_i32_16x16x64_i8 v[44:47], v[194:197], v[152:155], v[44:47]
	v_mfma_i32_16x16x64_i8 v[36:39], v[186:189], v[202:205], v[36:39]
	v_mfma_i32_16x16x64_i8 v[28:31], v[194:197], v[202:205], v[28:31]
	v_mfma_i32_16x16x64_i8 v[20:23], v[186:189], v[210:213], v[20:23]
	v_mfma_i32_16x16x64_i8 v[16:19], v[194:197], v[210:213], v[16:19]
	v_mfma_i32_16x16x64_i8 v[10:13], v[186:189], v[218:221], v[12:15]
	v_mfma_i32_16x16x64_i8 v[6:9], v[194:197], v[218:221], v[6:9]
	v_mfma_i32_16x16x64_i8 v[52:55], v[190:193], v[156:159], v[52:55]
	v_mfma_i32_16x16x64_i8 v[44:47], v[198:201], v[156:159], v[44:47]
	v_mfma_i32_16x16x64_i8 v[36:39], v[190:193], v[206:209], v[36:39]
	v_mfma_i32_16x16x64_i8 v[28:31], v[198:201], v[206:209], v[28:31]
	v_mfma_i32_16x16x64_i8 v[20:23], v[190:193], v[214:217], v[20:23]
	v_mfma_i32_16x16x64_i8 v[16:19], v[198:201], v[214:217], v[16:19]
	v_mfma_i32_16x16x64_i8 v[12:15], v[190:193], v[222:225], v[10:13]
	v_mfma_i32_16x16x64_i8 v[8:11], v[198:201], v[222:225], v[6:9]
	s_setprio 0
	s_barrier
	s_add_u32 s30, s30, 0x100
	s_addc_u32 s31, s31, 0
	s_add_u32 s72, s72, 0x100
	s_addc_u32 s73, s73, 0
	s_cmp_ge_i32 s8, s66
	s_cbranch_scc0 .Lp1i_top
	s_branch .Lp1i_epi

.LBB0_327:
	s_add_i32 s8, s74, 2
	s_add_u32 s34, s30, 0xfff80080
	s_addc_u32 s35, s31, -1
	s_cmp_eq_u32 s71, s74
	s_cselect_b32 s37, s67, s35
	s_cselect_b32 s36, s68, s34
	s_cselect_b32 s35, s69, s73
	s_cselect_b32 s34, s70, s72
	s_cmpk_lt_i32 s3, 0x56
	s_cselect_b32 s74, s56, 0x2b00
	s_mov_b32 s75, 0xac00
	s_cselect_b32 s76, s75, 0x4000
	s_sub_i32 s74, s74, s33
	v_min3_i32 v5, s74, v174, 2
	v_sub_u32_e32 v174, v174, v5
	v_readfirstlane_b32 s78, v5
	s_max_i32 s74, s78, 0
	s_add_i32 s74, s33, s74
	s_add_i32 s77, s74, -1
	s_min_i32 s74, s33, s77
	s_mul_hi_i32 s75, s76, s74
	s_mul_i32 s74, s76, s74
	s_add_u32 s74, s38, s74
	s_addc_u32 s75, s39, s75
	s_mul_hi_i32 s79, s76, s77
	s_mul_i32 s76, s76, s77
	s_add_u32 s76, s38, s76
	global_load_dwordx4 v[152:155], v173, s[74:75] nt
	s_addc_u32 s77, s39, s79
	global_load_dwordx4 v[156:159], v173, s[76:77] nt
	s_add_i32 s33, s78, s33
	ds_read_b128 v[160:163], v177
	ds_read_b128 v[164:167], v177 offset:1024
	ds_read_b128 v[168:171], v177 offset:2048
	ds_read_b128 v[182:185], v177 offset:3072
	ds_read_b128 v[186:189], v177 offset:16384
	ds_read_b128 v[190:193], v177 offset:17408
	ds_read_b128 v[194:197], v177 offset:18432
	ds_read_b128 v[198:201], v177 offset:19456
	s_add_i32 m0, s46, 0xc000
	ds_read_b128 v[202:205], v180
	ds_read_b128 v[206:209], v180 offset:1024
	ds_read_b128 v[210:213], v180 offset:2048
	ds_read_b128 v[214:217], v180 offset:3072
	ds_read_b128 v[218:221], v180 offset:4096
	ds_read_b128 v[222:225], v180 offset:5120
	ds_read_b128 v[226:229], v180 offset:6144
	global_load_lds_dwordx4 v146, s[30:31]
	s_add_i32 m0, s46, 0xe000
	ds_read_b128 v[230:233], v180 offset:7168
	global_load_lds_dwordx4 v148, s[30:31]
	s_waitcnt vmcnt(10)
	s_waitcnt lgkmcnt(0)
	s_barrier
	s_setprio 1
	s_waitcnt lgkmcnt(0)
	v_mfma_i32_16x16x64_i8 v[132:135], v[160:163], v[202:205], v[132:135]
	v_mfma_i32_16x16x64_i8 v[128:131], v[168:171], v[202:205], v[128:131]
	v_mfma_i32_16x16x64_i8 v[124:127], v[160:163], v[210:213], v[124:127]
	v_mfma_i32_16x16x64_i8 v[120:123], v[168:171], v[210:213], v[120:123]
	v_mfma_i32_16x16x64_i8 v[112:115], v[160:163], v[218:221], v[112:115]
	v_mfma_i32_16x16x64_i8 v[104:107], v[168:171], v[218:221], v[104:107]
	v_mfma_i32_16x16x64_i8 v[96:99], v[160:163], v[226:229], v[96:99]
	v_mfma_i32_16x16x64_i8 v[88:91], v[168:171], v[226:229], v[88:91]
	v_mfma_i32_16x16x64_i8 v[132:135], v[164:167], v[206:209], v[132:135]
	v_mfma_i32_16x16x64_i8 v[128:131], v[182:185], v[206:209], v[128:131]
	v_mfma_i32_16x16x64_i8 v[124:127], v[164:167], v[214:217], v[124:127]
	v_mfma_i32_16x16x64_i8 v[120:123], v[182:185], v[214:217], v[120:123]
	v_mfma_i32_16x16x64_i8 v[112:115], v[164:167], v[222:225], v[112:115]
	v_mfma_i32_16x16x64_i8 v[104:107], v[182:185], v[222:225], v[104:107]
	v_mfma_i32_16x16x64_i8 v[96:99], v[164:167], v[230:233], v[96:99]
	v_mfma_i32_16x16x64_i8 v[88:91], v[182:185], v[230:233], v[88:91]
	s_setprio 0
	s_setprio 1
	v_mfma_i32_16x16x64_i8 v[116:119], v[186:189], v[202:205], v[116:119]
	v_mfma_i32_16x16x64_i8 v[108:111], v[194:197], v[202:205], v[108:111]
	v_mfma_i32_16x16x64_i8 v[100:103], v[186:189], v[210:213], v[100:103]
	v_mfma_i32_16x16x64_i8 v[92:95], v[194:197], v[210:213], v[92:95]
	v_mfma_i32_16x16x64_i8 v[84:87], v[186:189], v[218:221], v[84:87]
	v_mfma_i32_16x16x64_i8 v[80:83], v[194:197], v[218:221], v[80:83]
	v_mfma_i32_16x16x64_i8 v[76:79], v[186:189], v[226:229], v[76:79]
	v_mfma_i32_16x16x64_i8 v[72:75], v[194:197], v[226:229], v[72:75]
	v_mfma_i32_16x16x64_i8 v[116:119], v[190:193], v[206:209], v[116:119]
	v_mfma_i32_16x16x64_i8 v[108:111], v[198:201], v[206:209], v[108:111]
	v_mfma_i32_16x16x64_i8 v[100:103], v[190:193], v[214:217], v[100:103]
	v_mfma_i32_16x16x64_i8 v[92:95], v[198:201], v[214:217], v[92:95]
	v_mfma_i32_16x16x64_i8 v[84:87], v[190:193], v[222:225], v[84:87]
	v_mfma_i32_16x16x64_i8 v[80:83], v[198:201], v[222:225], v[80:83]
	v_mfma_i32_16x16x64_i8 v[76:79], v[190:193], v[230:233], v[76:79]
	v_mfma_i32_16x16x64_i8 v[72:75], v[198:201], v[230:233], v[72:75]
	s_setprio 0
	s_barrier
	s_add_i32 s74, s57, s45
	s_mov_b32 m0, s74
	ds_read_b128 v[202:205], v180 offset:16384
	ds_read_b128 v[206:209], v180 offset:17408
	ds_read_b128 v[210:213], v180 offset:18432
	ds_read_b128 v[214:217], v180 offset:19456
	global_load_lds_dwordx4 v138, s[34:35]
	s_add_i32 m0, s74, 0x2000
	s_add_u32 s74, s34, 0x80000
	s_addc_u32 s75, s35, 0
	s_add_i32 s76, s58, s45
	global_load_lds_dwordx4 v142, s[34:35]
	s_mov_b32 m0, s76
	ds_read_b128 v[230:233], v180 offset:23552
	global_load_lds_dwordx4 v138, s[74:75]
	s_add_i32 m0, s76, 0x2000
	ds_read_b128 v[226:229], v180 offset:22528
	global_load_lds_dwordx4 v142, s[74:75]
	s_mov_b32 m0, s46
	ds_read_b128 v[222:225], v180 offset:21504
	global_load_lds_dwordx4 v136, s[36:37]
	s_mov_b32 m0, s47
	ds_read_b128 v[218:221], v180 offset:20480
	global_load_lds_dwordx4 v140, s[36:37]
	s_waitcnt vmcnt(10)
	s_waitcnt lgkmcnt(0)
	s_barrier
	s_setprio 1
	s_waitcnt lgkmcnt(0)
	v_mfma_i32_16x16x64_i8 v[68:71], v[160:163], v[202:205], v[68:71]
	v_mfma_i32_16x16x64_i8 v[64:67], v[168:171], v[202:205], v[64:67]
	v_mfma_i32_16x16x64_i8 v[60:63], v[160:163], v[210:213], v[60:63]
	v_mfma_i32_16x16x64_i8 v[56:59], v[168:171], v[210:213], v[56:59]
	v_mfma_i32_16x16x64_i8 v[48:51], v[160:163], v[218:221], v[48:51]
	v_mfma_i32_16x16x64_i8 v[40:43], v[168:171], v[218:221], v[40:43]
	v_mfma_i32_16x16x64_i8 v[32:35], v[160:163], v[226:229], v[32:35]
	v_mfma_i32_16x16x64_i8 v[24:27], v[168:171], v[226:229], v[24:27]
	v_mfma_i32_16x16x64_i8 v[68:71], v[164:167], v[206:209], v[68:71]
	v_mfma_i32_16x16x64_i8 v[64:67], v[182:185], v[206:209], v[64:67]
	v_mfma_i32_16x16x64_i8 v[60:63], v[164:167], v[214:217], v[60:63]
	v_mfma_i32_16x16x64_i8 v[56:59], v[182:185], v[214:217], v[56:59]
	v_mfma_i32_16x16x64_i8 v[48:51], v[164:167], v[222:225], v[48:51]
	v_mfma_i32_16x16x64_i8 v[40:43], v[182:185], v[222:225], v[40:43]
	v_mfma_i32_16x16x64_i8 v[32:35], v[164:167], v[230:233], v[32:35]
	v_mfma_i32_16x16x64_i8 v[24:27], v[182:185], v[230:233], v[24:27]
	s_setprio 0
	s_setprio 1
	v_mfma_i32_16x16x64_i8 v[52:55], v[186:189], v[202:205], v[52:55]
	v_mfma_i32_16x16x64_i8 v[44:47], v[194:197], v[202:205], v[44:47]
	v_mfma_i32_16x16x64_i8 v[36:39], v[186:189], v[210:213], v[36:39]
	v_mfma_i32_16x16x64_i8 v[28:31], v[194:197], v[210:213], v[28:31]
	v_mfma_i32_16x16x64_i8 v[20:23], v[186:189], v[218:221], v[20:23]
	v_mfma_i32_16x16x64_i8 v[16:19], v[194:197], v[218:221], v[16:19]
	v_mfma_i32_16x16x64_i8 v[12:15], v[186:189], v[226:229], v[12:15]
	v_mfma_i32_16x16x64_i8 v[6:9], v[194:197], v[226:229], v[8:11]
	v_mfma_i32_16x16x64_i8 v[52:55], v[190:193], v[206:209], v[52:55]
	v_mfma_i32_16x16x64_i8 v[44:47], v[198:201], v[206:209], v[44:47]
	v_mfma_i32_16x16x64_i8 v[36:39], v[190:193], v[214:217], v[36:39]
	v_mfma_i32_16x16x64_i8 v[28:31], v[198:201], v[214:217], v[28:31]
	v_mfma_i32_16x16x64_i8 v[20:23], v[190:193], v[222:225], v[20:23]
	v_mfma_i32_16x16x64_i8 v[16:19], v[198:201], v[222:225], v[16:19]
	v_mfma_i32_16x16x64_i8 v[12:15], v[190:193], v[230:233], v[12:15]
	v_mfma_i32_16x16x64_i8 v[6:9], v[198:201], v[230:233], v[6:9]
	s_setprio 0
	s_barrier
	s_add_i32 s74, 0, 0x18000
	s_add_i32 s75, 0, 0x1c000
	ds_read_b128 v[160:163], v177 offset:32768
	ds_read_b128 v[164:167], v177 offset:33792
	ds_read_b128 v[168:171], v177 offset:34816
	ds_read_b128 v[182:185], v177 offset:35840
	ds_read_b128 v[186:189], v177 offset:49152
	ds_read_b128 v[190:193], v177 offset:50176
	ds_read_b128 v[194:197], v177 offset:51200
	ds_read_b128 v[198:201], v177 offset:52224
	s_add_u32 s36, s36, 0x80000
	s_addc_u32 s37, s37, 0
	s_mov_b32 m0, s48
	ds_read_b128 v[202:205], v180 offset:32768
	ds_read_b128 v[206:209], v180 offset:33792
	ds_read_b128 v[210:213], v180 offset:34816
	ds_read_b128 v[214:217], v180 offset:35840
	ds_read_b128 v[218:221], v180 offset:36864
	ds_read_b128 v[222:225], v180 offset:37888
	ds_read_b128 v[226:229], v180 offset:38912
	global_load_lds_dwordx4 v136, s[36:37]
	s_mov_b32 m0, s49
	ds_read_b128 v[230:233], v180 offset:39936
	global_load_lds_dwordx4 v140, s[36:37]
	s_waitcnt vmcnt(8)
	s_waitcnt lgkmcnt(0)
	s_barrier
	s_setprio 1
	s_waitcnt lgkmcnt(0)
	v_mfma_i32_16x16x64_i8 v[132:135], v[160:163], v[202:205], v[132:135]
	v_mfma_i32_16x16x64_i8 v[128:131], v[168:171], v[202:205], v[128:131]
	v_mfma_i32_16x16x64_i8 v[124:127], v[160:163], v[210:213], v[124:127]
	v_mfma_i32_16x16x64_i8 v[120:123], v[168:171], v[210:213], v[120:123]
	v_mfma_i32_16x16x64_i8 v[112:115], v[160:163], v[218:221], v[112:115]
	v_max3_f32 v0, v0, |v152|, |v156|
	v_mfma_i32_16x16x64_i8 v[104:107], v[168:171], v[218:221], v[104:107]
	v_max3_f32 v1, v1, |v153|, |v157|
	v_mfma_i32_16x16x64_i8 v[96:99], v[160:163], v[226:229], v[96:99]
	v_max3_f32 v2, v2, |v154|, |v158|
	v_mfma_i32_16x16x64_i8 v[88:91], v[168:171], v[226:229], v[88:91]
	v_max3_f32 v3, v3, |v155|, |v159|
	v_mfma_i32_16x16x64_i8 v[132:135], v[164:167], v[206:209], v[132:135]
	v_mfma_i32_16x16x64_i8 v[128:131], v[182:185], v[206:209], v[128:131]
	v_mfma_i32_16x16x64_i8 v[124:127], v[164:167], v[214:217], v[124:127]
	v_mfma_i32_16x16x64_i8 v[120:123], v[182:185], v[214:217], v[120:123]
	v_mfma_i32_16x16x64_i8 v[112:115], v[164:167], v[222:225], v[112:115]
	v_mfma_i32_16x16x64_i8 v[104:107], v[182:185], v[222:225], v[104:107]
	v_mfma_i32_16x16x64_i8 v[96:99], v[164:167], v[230:233], v[96:99]
	v_mfma_i32_16x16x64_i8 v[88:91], v[182:185], v[230:233], v[88:91]
	s_setprio 0
	s_setprio 1
	v_mfma_i32_16x16x64_i8 v[116:119], v[186:189], v[202:205], v[116:119]
	v_mfma_i32_16x16x64_i8 v[108:111], v[194:197], v[202:205], v[108:111]
	v_mfma_i32_16x16x64_i8 v[100:103], v[186:189], v[210:213], v[100:103]
	v_mfma_i32_16x16x64_i8 v[92:95], v[194:197], v[210:213], v[92:95]
	v_mfma_i32_16x16x64_i8 v[84:87], v[186:189], v[218:221], v[84:87]
	v_mfma_i32_16x16x64_i8 v[80:83], v[194:197], v[218:221], v[80:83]
	v_mfma_i32_16x16x64_i8 v[76:79], v[186:189], v[226:229], v[76:79]
	v_mfma_i32_16x16x64_i8 v[72:75], v[194:197], v[226:229], v[72:75]
	v_mfma_i32_16x16x64_i8 v[116:119], v[190:193], v[206:209], v[116:119]
	v_mfma_i32_16x16x64_i8 v[108:111], v[198:201], v[206:209], v[108:111]
	v_mfma_i32_16x16x64_i8 v[100:103], v[190:193], v[214:217], v[100:103]
	v_mfma_i32_16x16x64_i8 v[92:95], v[198:201], v[214:217], v[92:95]
	v_mfma_i32_16x16x64_i8 v[84:87], v[190:193], v[222:225], v[84:87]
	v_mfma_i32_16x16x64_i8 v[80:83], v[198:201], v[222:225], v[80:83]
	v_mfma_i32_16x16x64_i8 v[76:79], v[190:193], v[230:233], v[76:79]
	v_mfma_i32_16x16x64_i8 v[72:75], v[198:201], v[230:233], v[72:75]
	s_setprio 0
	s_barrier
	s_add_u32 s98, s34, s14
	s_addc_u32 s99, s35, s15
	s_add_u32 s100, s36, s14
	s_addc_u32 s101, s37, s15
	s_sub_u32 s100, s100, 0x80000
	s_subb_u32 s101, s101, 0
	s_add_i32 s36, s74, s45
	s_mov_b32 m0, s36
	ds_read_b128 v[152:155], v180 offset:49152
	ds_read_b128 v[156:159], v180 offset:50176
	ds_read_b128 v[202:205], v180 offset:51200
	ds_read_b128 v[206:209], v180 offset:52224
	global_load_lds_dwordx4 v138, s[98:99]
	s_add_i32 m0, s36, 0x2000
	s_add_u32 s34, s34, 0x80080
	s_addc_u32 s35, s35, 0
	s_add_i32 s36, s75, s45
	global_load_lds_dwordx4 v142, s[98:99]
	s_mov_b32 m0, s36
	ds_read_b128 v[222:225], v180 offset:56320
	global_load_lds_dwordx4 v138, s[34:35]
	s_add_i32 m0, s36, 0x2000
	ds_read_b128 v[218:221], v180 offset:55296
	global_load_lds_dwordx4 v142, s[34:35]
	s_mov_b32 m0, s54
	ds_read_b128 v[214:217], v180 offset:54272
	global_load_lds_dwordx4 v136, s[100:101]
	s_mov_b32 m0, s55
	ds_read_b128 v[210:213], v180 offset:53248
	global_load_lds_dwordx4 v140, s[100:101]
	s_waitcnt vmcnt(8)
	s_waitcnt lgkmcnt(0)
	s_barrier
	s_setprio 1
	s_waitcnt lgkmcnt(0)
	v_mfma_i32_16x16x64_i8 v[68:71], v[160:163], v[152:155], v[68:71]
	v_mfma_i32_16x16x64_i8 v[64:67], v[168:171], v[152:155], v[64:67]
	v_mfma_i32_16x16x64_i8 v[60:63], v[160:163], v[202:205], v[60:63]
	v_mfma_i32_16x16x64_i8 v[56:59], v[168:171], v[202:205], v[56:59]
	v_mfma_i32_16x16x64_i8 v[48:51], v[160:163], v[210:213], v[48:51]
	v_mfma_i32_16x16x64_i8 v[40:43], v[168:171], v[210:213], v[40:43]
	v_mfma_i32_16x16x64_i8 v[32:35], v[160:163], v[218:221], v[32:35]
	v_mfma_i32_16x16x64_i8 v[24:27], v[168:171], v[218:221], v[24:27]
	v_mfma_i32_16x16x64_i8 v[68:71], v[164:167], v[156:159], v[68:71]
	v_mfma_i32_16x16x64_i8 v[64:67], v[182:185], v[156:159], v[64:67]
	v_mfma_i32_16x16x64_i8 v[60:63], v[164:167], v[206:209], v[60:63]
	v_mfma_i32_16x16x64_i8 v[56:59], v[182:185], v[206:209], v[56:59]
	v_mfma_i32_16x16x64_i8 v[48:51], v[164:167], v[214:217], v[48:51]
	v_mfma_i32_16x16x64_i8 v[40:43], v[182:185], v[214:217], v[40:43]
	v_mfma_i32_16x16x64_i8 v[32:35], v[164:167], v[222:225], v[32:35]
	v_mfma_i32_16x16x64_i8 v[24:27], v[182:185], v[222:225], v[24:27]
	s_setprio 0
	s_setprio 1
	v_mfma_i32_16x16x64_i8 v[52:55], v[186:189], v[152:155], v[52:55]
	v_mfma_i32_16x16x64_i8 v[44:47], v[194:197], v[152:155], v[44:47]
	v_mfma_i32_16x16x64_i8 v[36:39], v[186:189], v[202:205], v[36:39]
	v_mfma_i32_16x16x64_i8 v[28:31], v[194:197], v[202:205], v[28:31]
	v_mfma_i32_16x16x64_i8 v[20:23], v[186:189], v[210:213], v[20:23]
	v_mfma_i32_16x16x64_i8 v[16:19], v[194:197], v[210:213], v[16:19]
	v_mfma_i32_16x16x64_i8 v[10:13], v[186:189], v[218:221], v[12:15]
	v_mfma_i32_16x16x64_i8 v[6:9], v[194:197], v[218:221], v[6:9]
	v_mfma_i32_16x16x64_i8 v[52:55], v[190:193], v[156:159], v[52:55]
	v_mfma_i32_16x16x64_i8 v[44:47], v[198:201], v[156:159], v[44:47]
	v_mfma_i32_16x16x64_i8 v[36:39], v[190:193], v[206:209], v[36:39]
	v_mfma_i32_16x16x64_i8 v[28:31], v[198:201], v[206:209], v[28:31]
	v_mfma_i32_16x16x64_i8 v[20:23], v[190:193], v[214:217], v[20:23]
	v_mfma_i32_16x16x64_i8 v[16:19], v[198:201], v[214:217], v[16:19]
	v_mfma_i32_16x16x64_i8 v[12:15], v[190:193], v[222:225], v[10:13]
	v_mfma_i32_16x16x64_i8 v[8:11], v[198:201], v[222:225], v[6:9]
	s_setprio 0
	s_barrier
	s_add_u32 s30, s30, 0x100
	s_addc_u32 s31, s31, 0
	s_add_u32 s72, s72, 0x100
	s_addc_u32 s73, s73, 0
	s_cmp_ge_i32 s8, s66
	s_cbranch_scc0 .LBB0_312

.LBB0_1002:
	s_lshl_b32 s47, s6, 6
	s_lshl_b32 s11, s6, 13
	s_lshl_b32 s6, s7, 5
	s_and_b32 s48, s6, 0x60
	s_mov_b64 s[6:7], 0x80
	s_add_i32 m0, s43, 0x18000
	v_lshl_add_u64 v[8:9], v[8:9], 0, s[6:7]
	s_lshl_b32 s12, s48, 7
	s_waitcnt vmcnt(2)
	s_barrier
	global_load_lds_dwordx4 v[8:9], off
	v_lshl_add_u64 v[2:3], v[2:3], 0, s[6:7]
	s_add_i32 m0, s43, 0x1a000
	s_add_i32 s49, s43, 0x8000
	s_add_i32 s50, s43, 0xa000
	global_load_lds_dwordx4 v[2:3], off
	v_lshl_add_u64 v[0:1], v[0:1], 0, s[6:7]
	s_mov_b32 m0, s49
	s_add_u32 s8, s28, 0x100080
	global_load_lds_dwordx4 v[0:1], off
	v_lshl_add_u64 v[0:1], v[6:7], 0, s[6:7]
	s_mov_b32 m0, s50
	s_addc_u32 s9, s29, 0
	global_load_lds_dwordx4 v[0:1], off
	s_add_i32 m0, s43, 0x1c000
	v_lshl_add_u64 v[0:1], s[8:9], 0, v[138:139]
	global_load_lds_dwordx4 v[0:1], off
	v_lshl_add_u64 v[0:1], s[8:9], 0, v[142:143]
	s_add_i32 m0, s43, 0x1e000
	v_bfe_u32 v162, v5, 4, 2
	global_load_lds_dwordx4 v[0:1], off
	v_and_b32_e32 v161, 15, v5
	v_lshlrev_b32_e32 v0, 4, v162
	v_lshlrev_b32_e32 v1, 2, v5
	v_lshl_or_b32 v0, v161, 6, v0
	v_and_b32_e32 v1, 32, v1
	v_bitop3_b32 v8, v0, s11, v1 bitop3:0xde
	v_bitop3_b32 v163, v0, s12, v1 bitop3:0xde
	v_add_u32_e32 v163, 0x10000, v163
	v_lshlrev_b32_e32 v0, 2, v158
	v_ashrrev_i32_e32 v1, 31, v0
	v_lshl_add_u64 v[2:3], v[0:1], 2, s[96:97]
	v_lshlrev_b32_e32 v1, 16, v10
	s_mov_b64 s[12:13], 0xc0000
	v_and_b32_e32 v1, 0xfffe0000, v1
	v_lshl_add_u64 v[144:145], v[2:3], 0, s[12:13]
	v_lshl_add_u32 v1, v11, 13, v1
	v_and_b32_e32 v2, 1, v10
	v_lshl_or_b32 v1, v2, 6, v1
	v_lshl_add_u32 v146, v12, 1, v1
	v_lshlrev_b32_e32 v1, 16, v13
	v_and_b32_e32 v1, 0xfffe0000, v1
	s_cmpk_lt_u32 s10, 0x100
	v_lshl_add_u32 v1, v14, 13, v1
	v_and_b32_e32 v2, 1, v13
	s_waitcnt vmcnt(6)
	s_cselect_b64 s[10:11], -1, 0
	s_ashr_i32 s51, s47, 31
	v_and_b32_e32 v0, 0x7c, v0
	v_lshl_or_b32 v1, v2, 6, v1
	v_mov_b32_e32 v5, v4
	s_add_u32 s14, s96, 0x80000
	v_lshl_add_u32 v148, v15, 1, v1
	v_mov_b32_e32 v6, v4
	v_mov_b32_e32 v7, v4
	v_lshlrev_b32_e32 v150, 2, v0
	v_mov_b64_e32 v[0:1], v[4:5]
	s_mov_b32 s9, 0
	s_addc_u32 s15, s97, 0
	v_lshlrev_b32_e32 v164, 3, v158
	v_mov_b32_e32 v147, v4
	v_mov_b32_e32 v149, v4
	v_mov_b32_e32 v160, s16
	v_mov_b32_e32 v165, s38
	s_movk_i32 s52, 0x1000
	s_add_i32 s53, 0, 0x10000
	s_add_i32 s54, 0, 0x14000
	v_add_u32_e32 v166, 0, v8
	s_mov_b64 s[16:17], 0x40000
	v_mov_b64_e32 v[2:3], v[6:7]
	s_mov_b32 s55, 0
	s_barrier

.Lp4_body:
	s_add_i32 s8, s71, 2
	s_add_u32 s28, s26, 0xfff00080
	s_addc_u32 s29, s27, -1
	s_cmp_eq_u32 s68, s71
	s_cselect_b32 s31, s64, s29
	s_cselect_b32 s30, s65, s28
	s_cselect_b32 s29, s66, s70
	s_cselect_b32 s28, s67, s69
	ds_read_b128 v[172:175], v163
	ds_read_b128 v[176:179], v163 offset:1024
	ds_read_b128 v[180:183], v163 offset:2048
	ds_read_b128 v[184:187], v163 offset:3072
	ds_read_b128 v[188:191], v163 offset:16384
	ds_read_b128 v[192:195], v163 offset:17408
	ds_read_b128 v[196:199], v163 offset:18432
	ds_read_b128 v[200:203], v163 offset:19456
	s_add_i32 m0, s43, 0xc000
	ds_read_b128 v[204:207], v166
	ds_read_b128 v[208:211], v166 offset:1024
	ds_read_b128 v[212:215], v166 offset:2048
	ds_read_b128 v[216:219], v166 offset:3072
	ds_read_b128 v[220:223], v166 offset:4096
	ds_read_b128 v[224:227], v166 offset:5120
	ds_read_b128 v[236:239], v166 offset:6144
	global_load_lds_dwordx4 v146, s[26:27]
	s_add_i32 m0, s43, 0xe000
	ds_read_b128 v[240:243], v166 offset:7168
	global_load_lds_dwordx4 v148, s[26:27]
	s_waitcnt vmcnt(8)
	s_waitcnt lgkmcnt(0)
	s_barrier
	s_setprio 1
	s_waitcnt lgkmcnt(0)
	v_mfma_f32_16x16x32_bf16 v[132:135], v[172:175], v[204:207], v[132:135]
	v_mfma_f32_16x16x32_bf16 v[128:131], v[180:183], v[204:207], v[128:131]
	v_mfma_f32_16x16x32_bf16 v[116:119], v[172:175], v[212:215], v[116:119]
	v_mfma_f32_16x16x32_bf16 v[112:115], v[180:183], v[212:215], v[112:115]
	v_mfma_f32_16x16x32_bf16 v[100:103], v[172:175], v[220:223], v[100:103]
	v_mfma_f32_16x16x32_bf16 v[96:99], v[180:183], v[220:223], v[96:99]
	v_mfma_f32_16x16x32_bf16 v[84:87], v[172:175], v[236:239], v[84:87]
	v_mfma_f32_16x16x32_bf16 v[80:83], v[180:183], v[236:239], v[80:83]
	v_mfma_f32_16x16x32_bf16 v[132:135], v[176:179], v[208:211], v[132:135]
	v_mfma_f32_16x16x32_bf16 v[128:131], v[184:187], v[208:211], v[128:131]
	v_mfma_f32_16x16x32_bf16 v[116:119], v[176:179], v[216:219], v[116:119]
	v_mfma_f32_16x16x32_bf16 v[112:115], v[184:187], v[216:219], v[112:115]
	v_mfma_f32_16x16x32_bf16 v[100:103], v[176:179], v[224:227], v[100:103]
	v_mfma_f32_16x16x32_bf16 v[96:99], v[184:187], v[224:227], v[96:99]
	v_mfma_f32_16x16x32_bf16 v[84:87], v[176:179], v[240:243], v[84:87]
	v_mfma_f32_16x16x32_bf16 v[80:83], v[184:187], v[240:243], v[80:83]
	s_setprio 0
	s_setprio 1
	v_mfma_f32_16x16x32_bf16 v[124:127], v[188:191], v[204:207], v[124:127]
	v_mfma_f32_16x16x32_bf16 v[120:123], v[196:199], v[204:207], v[120:123]
	v_mfma_f32_16x16x32_bf16 v[108:111], v[188:191], v[212:215], v[108:111]
	v_mfma_f32_16x16x32_bf16 v[104:107], v[196:199], v[212:215], v[104:107]
	v_mfma_f32_16x16x32_bf16 v[92:95], v[188:191], v[220:223], v[92:95]
	v_mfma_f32_16x16x32_bf16 v[88:91], v[196:199], v[220:223], v[88:91]
	v_mfma_f32_16x16x32_bf16 v[76:79], v[188:191], v[236:239], v[76:79]
	v_mfma_f32_16x16x32_bf16 v[72:75], v[196:199], v[236:239], v[72:75]
	v_mfma_f32_16x16x32_bf16 v[124:127], v[192:195], v[208:211], v[124:127]
	v_mfma_f32_16x16x32_bf16 v[120:123], v[200:203], v[208:211], v[120:123]
	v_mfma_f32_16x16x32_bf16 v[108:111], v[192:195], v[216:219], v[108:111]
	v_mfma_f32_16x16x32_bf16 v[104:107], v[200:203], v[216:219], v[104:107]
	v_mfma_f32_16x16x32_bf16 v[92:95], v[192:195], v[224:227], v[92:95]
	v_mfma_f32_16x16x32_bf16 v[88:91], v[200:203], v[224:227], v[88:91]
	v_mfma_f32_16x16x32_bf16 v[76:79], v[192:195], v[240:243], v[76:79]
	v_mfma_f32_16x16x32_bf16 v[72:75], v[200:203], v[240:243], v[72:75]
	s_setprio 0
	s_barrier
	s_add_i32 s71, s53, s40
	s_mov_b32 m0, s71
	ds_read_b128 v[204:207], v166 offset:16384
	ds_read_b128 v[208:211], v166 offset:17408
	ds_read_b128 v[212:215], v166 offset:18432
	ds_read_b128 v[216:219], v166 offset:19456
	global_load_lds_dwordx4 v138, s[28:29]
	s_add_i32 m0, s71, 0x2000
	s_add_u32 s72, s28, 0x100000
	s_addc_u32 s73, s29, 0
	s_add_i32 s71, s54, s40
	global_load_lds_dwordx4 v142, s[28:29]
	s_mov_b32 m0, s71
	ds_read_b128 v[240:243], v166 offset:23552
	global_load_lds_dwordx4 v138, s[72:73]
	s_add_i32 m0, s71, 0x2000
	ds_read_b128 v[236:239], v166 offset:22528
	global_load_lds_dwordx4 v142, s[72:73]
	s_mov_b32 m0, s43
	ds_read_b128 v[224:227], v166 offset:21504
	global_load_lds_dwordx4 v136, s[30:31]
	s_mov_b32 m0, s44
	ds_read_b128 v[220:223], v166 offset:20480
	global_load_lds_dwordx4 v140, s[30:31]
	s_waitcnt vmcnt(8)
	s_waitcnt lgkmcnt(0)
	s_barrier
	s_setprio 1
	s_waitcnt lgkmcnt(0)
	v_mfma_f32_16x16x32_bf16 v[68:71], v[172:175], v[204:207], v[68:71]
	v_mfma_f32_16x16x32_bf16 v[64:67], v[180:183], v[204:207], v[64:67]
	v_mfma_f32_16x16x32_bf16 v[52:55], v[172:175], v[212:215], v[52:55]
	v_mfma_f32_16x16x32_bf16 v[48:51], v[180:183], v[212:215], v[48:51]
	v_mfma_f32_16x16x32_bf16 v[36:39], v[172:175], v[220:223], v[36:39]
	v_mfma_f32_16x16x32_bf16 v[32:35], v[180:183], v[220:223], v[32:35]
	v_mfma_f32_16x16x32_bf16 v[20:23], v[172:175], v[236:239], v[20:23]
	v_mfma_f32_16x16x32_bf16 v[16:19], v[180:183], v[236:239], v[16:19]
	v_mfma_f32_16x16x32_bf16 v[68:71], v[176:179], v[208:211], v[68:71]
	v_mfma_f32_16x16x32_bf16 v[64:67], v[184:187], v[208:211], v[64:67]
	v_mfma_f32_16x16x32_bf16 v[52:55], v[176:179], v[216:219], v[52:55]
	v_mfma_f32_16x16x32_bf16 v[48:51], v[184:187], v[216:219], v[48:51]
	v_mfma_f32_16x16x32_bf16 v[36:39], v[176:179], v[224:227], v[36:39]
	v_mfma_f32_16x16x32_bf16 v[32:35], v[184:187], v[224:227], v[32:35]
	v_mfma_f32_16x16x32_bf16 v[20:23], v[176:179], v[240:243], v[20:23]
	v_mfma_f32_16x16x32_bf16 v[16:19], v[184:187], v[240:243], v[16:19]
	s_setprio 0
	s_setprio 1
	v_mfma_f32_16x16x32_bf16 v[60:63], v[188:191], v[204:207], v[60:63]
	v_mfma_f32_16x16x32_bf16 v[56:59], v[196:199], v[204:207], v[56:59]
	v_mfma_f32_16x16x32_bf16 v[44:47], v[188:191], v[212:215], v[44:47]
	v_mfma_f32_16x16x32_bf16 v[40:43], v[196:199], v[212:215], v[40:43]
	v_mfma_f32_16x16x32_bf16 v[28:31], v[188:191], v[220:223], v[28:31]
	v_mfma_f32_16x16x32_bf16 v[24:27], v[196:199], v[220:223], v[24:27]
	v_mfma_f32_16x16x32_bf16 v[12:15], v[188:191], v[236:239], v[12:15]
	v_mfma_f32_16x16x32_bf16 v[6:9], v[196:199], v[236:239], v[8:11]
	v_mfma_f32_16x16x32_bf16 v[60:63], v[192:195], v[208:211], v[60:63]
	v_mfma_f32_16x16x32_bf16 v[56:59], v[200:203], v[208:211], v[56:59]
	v_mfma_f32_16x16x32_bf16 v[44:47], v[192:195], v[216:219], v[44:47]
	v_mfma_f32_16x16x32_bf16 v[40:43], v[200:203], v[216:219], v[40:43]
	v_mfma_f32_16x16x32_bf16 v[28:31], v[192:195], v[224:227], v[28:31]
	v_mfma_f32_16x16x32_bf16 v[24:27], v[200:203], v[224:227], v[24:27]
	v_mfma_f32_16x16x32_bf16 v[12:15], v[192:195], v[240:243], v[12:15]
	v_mfma_f32_16x16x32_bf16 v[6:9], v[200:203], v[240:243], v[6:9]
	s_setprio 0
	s_barrier
	s_add_i32 s71, 0, 0x18000
	s_add_i32 s72, 0, 0x1c000
	ds_read_b128 v[172:175], v163 offset:32768
	ds_read_b128 v[176:179], v163 offset:33792
	ds_read_b128 v[180:183], v163 offset:34816
	ds_read_b128 v[184:187], v163 offset:35840
	ds_read_b128 v[188:191], v163 offset:49152
	ds_read_b128 v[192:195], v163 offset:50176
	ds_read_b128 v[196:199], v163 offset:51200
	ds_read_b128 v[200:203], v163 offset:52224
	s_add_u32 s30, s30, 0x100000
	s_addc_u32 s31, s31, 0
	s_mov_b32 m0, s45
	ds_read_b128 v[204:207], v166 offset:32768
	ds_read_b128 v[208:211], v166 offset:33792
	ds_read_b128 v[212:215], v166 offset:34816
	ds_read_b128 v[216:219], v166 offset:35840
	ds_read_b128 v[220:223], v166 offset:36864
	ds_read_b128 v[224:227], v166 offset:37888
	ds_read_b128 v[236:239], v166 offset:38912
	global_load_lds_dwordx4 v136, s[30:31]
	s_mov_b32 m0, s46
	ds_read_b128 v[240:243], v166 offset:39936
	global_load_lds_dwordx4 v140, s[30:31]
	s_waitcnt vmcnt(8)
	s_waitcnt lgkmcnt(0)
	s_barrier
	s_setprio 1
	s_waitcnt lgkmcnt(0)
	v_mfma_f32_16x16x32_bf16 v[132:135], v[172:175], v[204:207], v[132:135]
	v_mfma_f32_16x16x32_bf16 v[128:131], v[180:183], v[204:207], v[128:131]
	v_mfma_f32_16x16x32_bf16 v[116:119], v[172:175], v[212:215], v[116:119]
	v_mfma_f32_16x16x32_bf16 v[112:115], v[180:183], v[212:215], v[112:115]
	v_mfma_f32_16x16x32_bf16 v[100:103], v[172:175], v[220:223], v[100:103]
	v_mfma_f32_16x16x32_bf16 v[96:99], v[180:183], v[220:223], v[96:99]
	v_mfma_f32_16x16x32_bf16 v[84:87], v[172:175], v[236:239], v[84:87]
	v_mfma_f32_16x16x32_bf16 v[80:83], v[180:183], v[236:239], v[80:83]
	v_mfma_f32_16x16x32_bf16 v[132:135], v[176:179], v[208:211], v[132:135]
	v_mfma_f32_16x16x32_bf16 v[128:131], v[184:187], v[208:211], v[128:131]
	v_mfma_f32_16x16x32_bf16 v[116:119], v[176:179], v[216:219], v[116:119]
	v_mfma_f32_16x16x32_bf16 v[112:115], v[184:187], v[216:219], v[112:115]
	v_mfma_f32_16x16x32_bf16 v[100:103], v[176:179], v[224:227], v[100:103]
	v_mfma_f32_16x16x32_bf16 v[96:99], v[184:187], v[224:227], v[96:99]
	v_mfma_f32_16x16x32_bf16 v[84:87], v[176:179], v[240:243], v[84:87]
	v_mfma_f32_16x16x32_bf16 v[80:83], v[184:187], v[240:243], v[80:83]
	s_setprio 0
	s_setprio 1
	v_mfma_f32_16x16x32_bf16 v[124:127], v[188:191], v[204:207], v[124:127]
	v_mfma_f32_16x16x32_bf16 v[120:123], v[196:199], v[204:207], v[120:123]
	v_mfma_f32_16x16x32_bf16 v[108:111], v[188:191], v[212:215], v[108:111]
	v_mfma_f32_16x16x32_bf16 v[104:107], v[196:199], v[212:215], v[104:107]
	v_mfma_f32_16x16x32_bf16 v[92:95], v[188:191], v[220:223], v[92:95]
	v_mfma_f32_16x16x32_bf16 v[88:91], v[196:199], v[220:223], v[88:91]
	v_mfma_f32_16x16x32_bf16 v[76:79], v[188:191], v[236:239], v[76:79]
	v_mfma_f32_16x16x32_bf16 v[72:75], v[196:199], v[236:239], v[72:75]
	v_mfma_f32_16x16x32_bf16 v[124:127], v[192:195], v[208:211], v[124:127]
	v_mfma_f32_16x16x32_bf16 v[120:123], v[200:203], v[208:211], v[120:123]
	v_mfma_f32_16x16x32_bf16 v[108:111], v[192:195], v[216:219], v[108:111]
	v_mfma_f32_16x16x32_bf16 v[104:107], v[200:203], v[216:219], v[104:107]
	v_mfma_f32_16x16x32_bf16 v[92:95], v[192:195], v[224:227], v[92:95]
	v_mfma_f32_16x16x32_bf16 v[88:91], v[200:203], v[224:227], v[88:91]
	v_mfma_f32_16x16x32_bf16 v[76:79], v[192:195], v[240:243], v[76:79]
	v_mfma_f32_16x16x32_bf16 v[72:75], v[200:203], v[240:243], v[72:75]
	s_setprio 0
	s_barrier
	s_add_u32 s74, s28, s6
	s_addc_u32 s75, s29, s7
	s_add_u32 s76, s30, s6
	s_addc_u32 s77, s31, s7
	s_sub_u32 s76, s76, 0x100000
	s_subb_u32 s77, s77, 0
	s_add_i32 s30, s71, s40
	s_mov_b32 m0, s30
	ds_read_b128 v[152:155], v166 offset:49152
	ds_read_b128 v[168:171], v166 offset:50176
	ds_read_b128 v[204:207], v166 offset:51200
	ds_read_b128 v[208:211], v166 offset:52224
	global_load_lds_dwordx4 v138, s[74:75]
	s_add_i32 m0, s30, 0x2000
	s_add_u32 s28, s28, 0x100080
	s_addc_u32 s29, s29, 0
	s_add_i32 s30, s72, s40
	global_load_lds_dwordx4 v142, s[74:75]
	s_mov_b32 m0, s30
	ds_read_b128 v[224:227], v166 offset:56320
	global_load_lds_dwordx4 v138, s[28:29]
	s_add_i32 m0, s30, 0x2000
	ds_read_b128 v[220:223], v166 offset:55296
	global_load_lds_dwordx4 v142, s[28:29]
	s_mov_b32 m0, s49
	ds_read_b128 v[216:219], v166 offset:54272
	global_load_lds_dwordx4 v136, s[76:77]
	s_mov_b32 m0, s50
	ds_read_b128 v[212:215], v166 offset:53248
	global_load_lds_dwordx4 v140, s[76:77]
	s_waitcnt vmcnt(8)
	s_waitcnt lgkmcnt(0)
	s_barrier
	s_setprio 1
	s_waitcnt lgkmcnt(0)
	v_mfma_f32_16x16x32_bf16 v[68:71], v[172:175], v[152:155], v[68:71]
	v_mfma_f32_16x16x32_bf16 v[64:67], v[180:183], v[152:155], v[64:67]
	v_mfma_f32_16x16x32_bf16 v[52:55], v[172:175], v[204:207], v[52:55]
	v_mfma_f32_16x16x32_bf16 v[48:51], v[180:183], v[204:207], v[48:51]
	v_mfma_f32_16x16x32_bf16 v[36:39], v[172:175], v[212:215], v[36:39]
	v_mfma_f32_16x16x32_bf16 v[32:35], v[180:183], v[212:215], v[32:35]
	v_mfma_f32_16x16x32_bf16 v[20:23], v[172:175], v[220:223], v[20:23]
	v_mfma_f32_16x16x32_bf16 v[16:19], v[180:183], v[220:223], v[16:19]
	v_mfma_f32_16x16x32_bf16 v[68:71], v[176:179], v[168:171], v[68:71]
	v_mfma_f32_16x16x32_bf16 v[64:67], v[184:187], v[168:171], v[64:67]
	v_mfma_f32_16x16x32_bf16 v[52:55], v[176:179], v[208:211], v[52:55]
	v_mfma_f32_16x16x32_bf16 v[48:51], v[184:187], v[208:211], v[48:51]
	v_mfma_f32_16x16x32_bf16 v[36:39], v[176:179], v[216:219], v[36:39]
	v_mfma_f32_16x16x32_bf16 v[32:35], v[184:187], v[216:219], v[32:35]
	v_mfma_f32_16x16x32_bf16 v[20:23], v[176:179], v[224:227], v[20:23]
	v_mfma_f32_16x16x32_bf16 v[16:19], v[184:187], v[224:227], v[16:19]
	s_setprio 0
	s_setprio 1
	v_mfma_f32_16x16x32_bf16 v[60:63], v[188:191], v[152:155], v[60:63]
	v_mfma_f32_16x16x32_bf16 v[56:59], v[196:199], v[152:155], v[56:59]
	v_mfma_f32_16x16x32_bf16 v[44:47], v[188:191], v[204:207], v[44:47]
	v_mfma_f32_16x16x32_bf16 v[40:43], v[196:199], v[204:207], v[40:43]
	v_mfma_f32_16x16x32_bf16 v[28:31], v[188:191], v[212:215], v[28:31]
	v_mfma_f32_16x16x32_bf16 v[24:27], v[196:199], v[212:215], v[24:27]
	v_mfma_f32_16x16x32_bf16 v[10:13], v[188:191], v[220:223], v[12:15]
	v_mfma_f32_16x16x32_bf16 v[6:9], v[196:199], v[220:223], v[6:9]
	v_mfma_f32_16x16x32_bf16 v[60:63], v[192:195], v[168:171], v[60:63]
	v_mfma_f32_16x16x32_bf16 v[56:59], v[200:203], v[168:171], v[56:59]
	v_mfma_f32_16x16x32_bf16 v[44:47], v[192:195], v[208:211], v[44:47]
	v_mfma_f32_16x16x32_bf16 v[40:43], v[200:203], v[208:211], v[40:43]
	v_mfma_f32_16x16x32_bf16 v[28:31], v[192:195], v[216:219], v[28:31]
	v_mfma_f32_16x16x32_bf16 v[24:27], v[200:203], v[216:219], v[24:27]
	v_mfma_f32_16x16x32_bf16 v[12:15], v[192:195], v[224:227], v[10:13]
	v_mfma_f32_16x16x32_bf16 v[8:11], v[200:203], v[224:227], v[6:9]
	s_setprio 0
	s_barrier
	s_add_u32 s26, s26, 0x100
	s_addc_u32 s27, s27, 0
	s_add_u32 s69, s69, 0x100
	s_addc_u32 s70, s70, 0
	s_cmp_ge_i32 s8, s63
	s_cbranch_scc0 .Lp4_top
	s_branch .Lp4_epi

.LBB0_1033:
	s_add_i32 s8, s71, 2
	s_add_u32 s28, s26, 0xfff00080
	s_addc_u32 s29, s27, -1
	s_cmp_eq_u32 s68, s71
	s_cselect_b32 s31, s64, s29
	s_cselect_b32 s30, s65, s28
	s_cselect_b32 s29, s66, s70
	s_cselect_b32 s28, s67, s69
	s_cmpk_lt_i32 s3, 0x56
	s_cselect_b32 s71, s52, 0x2b00
	s_mov_b32 s72, 0xac00
	s_cselect_b32 s74, s72, 0x4000
	s_sub_i32 s71, s71, s33
	v_min3_i32 v5, s71, v160, 2
	v_sub_u32_e32 v160, v160, v5
	v_readfirstlane_b32 s71, v5
	s_max_i32 s72, s71, 0
	s_add_i32 s72, s33, s72
	s_add_i32 s75, s72, -1
	s_min_i32 s72, s33, s75
	s_mul_hi_i32 s73, s74, s72
	s_mul_i32 s72, s74, s72
	s_add_u32 s72, s34, s72
	s_addc_u32 s73, s35, s73
	s_mul_hi_i32 s76, s74, s75
	s_mul_i32 s74, s74, s75
	s_add_u32 s74, s34, s74
	global_load_dwordx4 v[152:155], v159, s[72:73] nt
	s_addc_u32 s75, s35, s76
	global_load_dwordx4 v[168:171], v159, s[74:75] nt
	s_add_i32 s33, s71, s33
	ds_read_b128 v[172:175], v163
	ds_read_b128 v[176:179], v163 offset:1024
	ds_read_b128 v[180:183], v163 offset:2048
	ds_read_b128 v[184:187], v163 offset:3072
	ds_read_b128 v[188:191], v163 offset:16384
	ds_read_b128 v[192:195], v163 offset:17408
	ds_read_b128 v[196:199], v163 offset:18432
	ds_read_b128 v[200:203], v163 offset:19456
	s_add_i32 m0, s43, 0xc000
	ds_read_b128 v[204:207], v166
	ds_read_b128 v[208:211], v166 offset:1024
	ds_read_b128 v[212:215], v166 offset:2048
	ds_read_b128 v[216:219], v166 offset:3072
	ds_read_b128 v[220:223], v166 offset:4096
	ds_read_b128 v[224:227], v166 offset:5120
	ds_read_b128 v[236:239], v166 offset:6144
	global_load_lds_dwordx4 v146, s[26:27]
	s_add_i32 m0, s43, 0xe000
	ds_read_b128 v[240:243], v166 offset:7168
	global_load_lds_dwordx4 v148, s[26:27]
	s_waitcnt vmcnt(10)
	s_waitcnt lgkmcnt(0)
	s_barrier
	s_setprio 1
	s_waitcnt lgkmcnt(0)
	v_mfma_f32_16x16x32_bf16 v[132:135], v[172:175], v[204:207], v[132:135]
	v_mfma_f32_16x16x32_bf16 v[128:131], v[180:183], v[204:207], v[128:131]
	v_mfma_f32_16x16x32_bf16 v[116:119], v[172:175], v[212:215], v[116:119]
	v_mfma_f32_16x16x32_bf16 v[112:115], v[180:183], v[212:215], v[112:115]
	v_mfma_f32_16x16x32_bf16 v[100:103], v[172:175], v[220:223], v[100:103]
	v_mfma_f32_16x16x32_bf16 v[96:99], v[180:183], v[220:223], v[96:99]
	v_mfma_f32_16x16x32_bf16 v[84:87], v[172:175], v[236:239], v[84:87]
	v_mfma_f32_16x16x32_bf16 v[80:83], v[180:183], v[236:239], v[80:83]
	v_mfma_f32_16x16x32_bf16 v[132:135], v[176:179], v[208:211], v[132:135]
	v_mfma_f32_16x16x32_bf16 v[128:131], v[184:187], v[208:211], v[128:131]
	v_mfma_f32_16x16x32_bf16 v[116:119], v[176:179], v[216:219], v[116:119]
	v_mfma_f32_16x16x32_bf16 v[112:115], v[184:187], v[216:219], v[112:115]
	v_mfma_f32_16x16x32_bf16 v[100:103], v[176:179], v[224:227], v[100:103]
	v_mfma_f32_16x16x32_bf16 v[96:99], v[184:187], v[224:227], v[96:99]
	v_mfma_f32_16x16x32_bf16 v[84:87], v[176:179], v[240:243], v[84:87]
	v_mfma_f32_16x16x32_bf16 v[80:83], v[184:187], v[240:243], v[80:83]
	s_setprio 0
	s_setprio 1
	v_mfma_f32_16x16x32_bf16 v[124:127], v[188:191], v[204:207], v[124:127]
	v_mfma_f32_16x16x32_bf16 v[120:123], v[196:199], v[204:207], v[120:123]
	v_mfma_f32_16x16x32_bf16 v[108:111], v[188:191], v[212:215], v[108:111]
	v_mfma_f32_16x16x32_bf16 v[104:107], v[196:199], v[212:215], v[104:107]
	v_mfma_f32_16x16x32_bf16 v[92:95], v[188:191], v[220:223], v[92:95]
	v_mfma_f32_16x16x32_bf16 v[88:91], v[196:199], v[220:223], v[88:91]
	v_mfma_f32_16x16x32_bf16 v[76:79], v[188:191], v[236:239], v[76:79]
	v_mfma_f32_16x16x32_bf16 v[72:75], v[196:199], v[236:239], v[72:75]
	v_mfma_f32_16x16x32_bf16 v[124:127], v[192:195], v[208:211], v[124:127]
	v_mfma_f32_16x16x32_bf16 v[120:123], v[200:203], v[208:211], v[120:123]
	v_mfma_f32_16x16x32_bf16 v[108:111], v[192:195], v[216:219], v[108:111]
	v_mfma_f32_16x16x32_bf16 v[104:107], v[200:203], v[216:219], v[104:107]
	v_mfma_f32_16x16x32_bf16 v[92:95], v[192:195], v[224:227], v[92:95]
	v_mfma_f32_16x16x32_bf16 v[88:91], v[200:203], v[224:227], v[88:91]
	v_mfma_f32_16x16x32_bf16 v[76:79], v[192:195], v[240:243], v[76:79]
	v_mfma_f32_16x16x32_bf16 v[72:75], v[200:203], v[240:243], v[72:75]
	s_setprio 0
	s_barrier
	s_add_i32 s71, s53, s40
	s_mov_b32 m0, s71
	ds_read_b128 v[204:207], v166 offset:16384
	ds_read_b128 v[208:211], v166 offset:17408
	ds_read_b128 v[212:215], v166 offset:18432
	ds_read_b128 v[216:219], v166 offset:19456
	global_load_lds_dwordx4 v138, s[28:29]
	s_add_i32 m0, s71, 0x2000
	s_add_u32 s72, s28, 0x100000
	s_addc_u32 s73, s29, 0
	s_add_i32 s71, s54, s40
	global_load_lds_dwordx4 v142, s[28:29]
	s_mov_b32 m0, s71
	ds_read_b128 v[240:243], v166 offset:23552
	global_load_lds_dwordx4 v138, s[72:73]
	s_add_i32 m0, s71, 0x2000
	ds_read_b128 v[236:239], v166 offset:22528
	global_load_lds_dwordx4 v142, s[72:73]
	s_mov_b32 m0, s43
	ds_read_b128 v[224:227], v166 offset:21504
	global_load_lds_dwordx4 v136, s[30:31]
	s_mov_b32 m0, s44
	ds_read_b128 v[220:223], v166 offset:20480
	global_load_lds_dwordx4 v140, s[30:31]
	s_waitcnt vmcnt(10)
	s_waitcnt lgkmcnt(0)
	s_barrier
	s_setprio 1
	s_waitcnt lgkmcnt(0)
	v_mfma_f32_16x16x32_bf16 v[68:71], v[172:175], v[204:207], v[68:71]
	v_mfma_f32_16x16x32_bf16 v[64:67], v[180:183], v[204:207], v[64:67]
	v_mfma_f32_16x16x32_bf16 v[52:55], v[172:175], v[212:215], v[52:55]
	v_mfma_f32_16x16x32_bf16 v[48:51], v[180:183], v[212:215], v[48:51]
	v_mfma_f32_16x16x32_bf16 v[36:39], v[172:175], v[220:223], v[36:39]
	v_mfma_f32_16x16x32_bf16 v[32:35], v[180:183], v[220:223], v[32:35]
	v_mfma_f32_16x16x32_bf16 v[20:23], v[172:175], v[236:239], v[20:23]
	v_mfma_f32_16x16x32_bf16 v[16:19], v[180:183], v[236:239], v[16:19]
	v_mfma_f32_16x16x32_bf16 v[68:71], v[176:179], v[208:211], v[68:71]
	v_mfma_f32_16x16x32_bf16 v[64:67], v[184:187], v[208:211], v[64:67]
	v_mfma_f32_16x16x32_bf16 v[52:55], v[176:179], v[216:219], v[52:55]
	v_mfma_f32_16x16x32_bf16 v[48:51], v[184:187], v[216:219], v[48:51]
	v_mfma_f32_16x16x32_bf16 v[36:39], v[176:179], v[224:227], v[36:39]
	v_mfma_f32_16x16x32_bf16 v[32:35], v[184:187], v[224:227], v[32:35]
	v_mfma_f32_16x16x32_bf16 v[20:23], v[176:179], v[240:243], v[20:23]
	v_mfma_f32_16x16x32_bf16 v[16:19], v[184:187], v[240:243], v[16:19]
	s_setprio 0
	s_setprio 1
	v_mfma_f32_16x16x32_bf16 v[60:63], v[188:191], v[204:207], v[60:63]
	v_mfma_f32_16x16x32_bf16 v[56:59], v[196:199], v[204:207], v[56:59]
	v_mfma_f32_16x16x32_bf16 v[44:47], v[188:191], v[212:215], v[44:47]
	v_mfma_f32_16x16x32_bf16 v[40:43], v[196:199], v[212:215], v[40:43]
	v_mfma_f32_16x16x32_bf16 v[28:31], v[188:191], v[220:223], v[28:31]
	v_mfma_f32_16x16x32_bf16 v[24:27], v[196:199], v[220:223], v[24:27]
	v_mfma_f32_16x16x32_bf16 v[12:15], v[188:191], v[236:239], v[12:15]
	v_mfma_f32_16x16x32_bf16 v[6:9], v[196:199], v[236:239], v[8:11]
	v_mfma_f32_16x16x32_bf16 v[60:63], v[192:195], v[208:211], v[60:63]
	v_mfma_f32_16x16x32_bf16 v[56:59], v[200:203], v[208:211], v[56:59]
	v_mfma_f32_16x16x32_bf16 v[44:47], v[192:195], v[216:219], v[44:47]
	v_mfma_f32_16x16x32_bf16 v[40:43], v[200:203], v[216:219], v[40:43]
	v_mfma_f32_16x16x32_bf16 v[28:31], v[192:195], v[224:227], v[28:31]
	v_mfma_f32_16x16x32_bf16 v[24:27], v[200:203], v[224:227], v[24:27]
	v_mfma_f32_16x16x32_bf16 v[12:15], v[192:195], v[240:243], v[12:15]
	v_mfma_f32_16x16x32_bf16 v[6:9], v[200:203], v[240:243], v[6:9]
	s_setprio 0
	s_barrier
	s_add_i32 s71, 0, 0x18000
	s_add_i32 s72, 0, 0x1c000
	ds_read_b128 v[172:175], v163 offset:32768
	ds_read_b128 v[176:179], v163 offset:33792
	ds_read_b128 v[180:183], v163 offset:34816
	ds_read_b128 v[184:187], v163 offset:35840
	ds_read_b128 v[188:191], v163 offset:49152
	ds_read_b128 v[192:195], v163 offset:50176
	ds_read_b128 v[196:199], v163 offset:51200
	ds_read_b128 v[200:203], v163 offset:52224
	s_add_u32 s30, s30, 0x100000
	s_addc_u32 s31, s31, 0
	s_mov_b32 m0, s45
	ds_read_b128 v[204:207], v166 offset:32768
	ds_read_b128 v[208:211], v166 offset:33792
	ds_read_b128 v[212:215], v166 offset:34816
	ds_read_b128 v[216:219], v166 offset:35840
	ds_read_b128 v[220:223], v166 offset:36864
	ds_read_b128 v[224:227], v166 offset:37888
	ds_read_b128 v[236:239], v166 offset:38912
	global_load_lds_dwordx4 v136, s[30:31]
	s_mov_b32 m0, s46
	ds_read_b128 v[240:243], v166 offset:39936
	global_load_lds_dwordx4 v140, s[30:31]
	s_waitcnt vmcnt(8)
	s_waitcnt lgkmcnt(0)
	s_barrier
	s_setprio 1
	s_waitcnt lgkmcnt(0)
	v_mfma_f32_16x16x32_bf16 v[132:135], v[172:175], v[204:207], v[132:135]
	v_mfma_f32_16x16x32_bf16 v[128:131], v[180:183], v[204:207], v[128:131]
	v_mfma_f32_16x16x32_bf16 v[116:119], v[172:175], v[212:215], v[116:119]
	v_mfma_f32_16x16x32_bf16 v[112:115], v[180:183], v[212:215], v[112:115]
	v_mfma_f32_16x16x32_bf16 v[100:103], v[172:175], v[220:223], v[100:103]
	v_max3_f32 v0, v0, |v152|, |v168|
	v_mfma_f32_16x16x32_bf16 v[96:99], v[180:183], v[220:223], v[96:99]
	v_max3_f32 v1, v1, |v153|, |v169|
	v_mfma_f32_16x16x32_bf16 v[84:87], v[172:175], v[236:239], v[84:87]
	v_max3_f32 v2, v2, |v154|, |v170|
	v_mfma_f32_16x16x32_bf16 v[80:83], v[180:183], v[236:239], v[80:83]
	v_max3_f32 v3, v3, |v155|, |v171|
	v_mfma_f32_16x16x32_bf16 v[132:135], v[176:179], v[208:211], v[132:135]
	v_mfma_f32_16x16x32_bf16 v[128:131], v[184:187], v[208:211], v[128:131]
	v_mfma_f32_16x16x32_bf16 v[116:119], v[176:179], v[216:219], v[116:119]
	v_mfma_f32_16x16x32_bf16 v[112:115], v[184:187], v[216:219], v[112:115]
	v_mfma_f32_16x16x32_bf16 v[100:103], v[176:179], v[224:227], v[100:103]
	v_mfma_f32_16x16x32_bf16 v[96:99], v[184:187], v[224:227], v[96:99]
	v_mfma_f32_16x16x32_bf16 v[84:87], v[176:179], v[240:243], v[84:87]
	v_mfma_f32_16x16x32_bf16 v[80:83], v[184:187], v[240:243], v[80:83]
	s_setprio 0
	s_setprio 1
	v_mfma_f32_16x16x32_bf16 v[124:127], v[188:191], v[204:207], v[124:127]
	v_mfma_f32_16x16x32_bf16 v[120:123], v[196:199], v[204:207], v[120:123]
	v_mfma_f32_16x16x32_bf16 v[108:111], v[188:191], v[212:215], v[108:111]
	v_mfma_f32_16x16x32_bf16 v[104:107], v[196:199], v[212:215], v[104:107]
	v_mfma_f32_16x16x32_bf16 v[92:95], v[188:191], v[220:223], v[92:95]
	v_mfma_f32_16x16x32_bf16 v[88:91], v[196:199], v[220:223], v[88:91]
	v_mfma_f32_16x16x32_bf16 v[76:79], v[188:191], v[236:239], v[76:79]
	v_mfma_f32_16x16x32_bf16 v[72:75], v[196:199], v[236:239], v[72:75]
	v_mfma_f32_16x16x32_bf16 v[124:127], v[192:195], v[208:211], v[124:127]
	v_mfma_f32_16x16x32_bf16 v[120:123], v[200:203], v[208:211], v[120:123]
	v_mfma_f32_16x16x32_bf16 v[108:111], v[192:195], v[216:219], v[108:111]
	v_mfma_f32_16x16x32_bf16 v[104:107], v[200:203], v[216:219], v[104:107]
	v_mfma_f32_16x16x32_bf16 v[92:95], v[192:195], v[224:227], v[92:95]
	v_mfma_f32_16x16x32_bf16 v[88:91], v[200:203], v[224:227], v[88:91]
	v_mfma_f32_16x16x32_bf16 v[76:79], v[192:195], v[240:243], v[76:79]
	v_mfma_f32_16x16x32_bf16 v[72:75], v[200:203], v[240:243], v[72:75]
	s_setprio 0
	s_barrier
	s_add_u32 s74, s28, s6
	s_addc_u32 s75, s29, s7
	s_add_u32 s76, s30, s6
	s_addc_u32 s77, s31, s7
	s_sub_u32 s76, s76, 0x100000
	s_subb_u32 s77, s77, 0
	s_add_i32 s30, s71, s40
	s_mov_b32 m0, s30
	ds_read_b128 v[152:155], v166 offset:49152
	ds_read_b128 v[168:171], v166 offset:50176
	ds_read_b128 v[204:207], v166 offset:51200
	ds_read_b128 v[208:211], v166 offset:52224
	global_load_lds_dwordx4 v138, s[74:75]
	s_add_i32 m0, s30, 0x2000
	s_add_u32 s28, s28, 0x100080
	s_addc_u32 s29, s29, 0
	s_add_i32 s30, s72, s40
	global_load_lds_dwordx4 v142, s[74:75]
	s_mov_b32 m0, s30
	ds_read_b128 v[224:227], v166 offset:56320
	global_load_lds_dwordx4 v138, s[28:29]
	s_add_i32 m0, s30, 0x2000
	ds_read_b128 v[220:223], v166 offset:55296
	global_load_lds_dwordx4 v142, s[28:29]
	s_mov_b32 m0, s49
	ds_read_b128 v[216:219], v166 offset:54272
	global_load_lds_dwordx4 v136, s[76:77]
	s_mov_b32 m0, s50
	ds_read_b128 v[212:215], v166 offset:53248
	global_load_lds_dwordx4 v140, s[76:77]
	s_waitcnt vmcnt(8)
	s_waitcnt lgkmcnt(0)
	s_barrier
	s_setprio 1
	s_waitcnt lgkmcnt(0)
	v_mfma_f32_16x16x32_bf16 v[68:71], v[172:175], v[152:155], v[68:71]
	v_mfma_f32_16x16x32_bf16 v[64:67], v[180:183], v[152:155], v[64:67]
	v_mfma_f32_16x16x32_bf16 v[52:55], v[172:175], v[204:207], v[52:55]
	v_mfma_f32_16x16x32_bf16 v[48:51], v[180:183], v[204:207], v[48:51]
	v_mfma_f32_16x16x32_bf16 v[36:39], v[172:175], v[212:215], v[36:39]
	v_mfma_f32_16x16x32_bf16 v[32:35], v[180:183], v[212:215], v[32:35]
	v_mfma_f32_16x16x32_bf16 v[20:23], v[172:175], v[220:223], v[20:23]
	v_mfma_f32_16x16x32_bf16 v[16:19], v[180:183], v[220:223], v[16:19]
	v_mfma_f32_16x16x32_bf16 v[68:71], v[176:179], v[168:171], v[68:71]
	v_mfma_f32_16x16x32_bf16 v[64:67], v[184:187], v[168:171], v[64:67]
	v_mfma_f32_16x16x32_bf16 v[52:55], v[176:179], v[208:211], v[52:55]
	v_mfma_f32_16x16x32_bf16 v[48:51], v[184:187], v[208:211], v[48:51]
	v_mfma_f32_16x16x32_bf16 v[36:39], v[176:179], v[216:219], v[36:39]
	v_mfma_f32_16x16x32_bf16 v[32:35], v[184:187], v[216:219], v[32:35]
	v_mfma_f32_16x16x32_bf16 v[20:23], v[176:179], v[224:227], v[20:23]
	v_mfma_f32_16x16x32_bf16 v[16:19], v[184:187], v[224:227], v[16:19]
	s_setprio 0
	s_setprio 1
	v_mfma_f32_16x16x32_bf16 v[60:63], v[188:191], v[152:155], v[60:63]
	v_mfma_f32_16x16x32_bf16 v[56:59], v[196:199], v[152:155], v[56:59]
	v_mfma_f32_16x16x32_bf16 v[44:47], v[188:191], v[204:207], v[44:47]
	v_mfma_f32_16x16x32_bf16 v[40:43], v[196:199], v[204:207], v[40:43]
	v_mfma_f32_16x16x32_bf16 v[28:31], v[188:191], v[212:215], v[28:31]
	v_mfma_f32_16x16x32_bf16 v[24:27], v[196:199], v[212:215], v[24:27]
	v_mfma_f32_16x16x32_bf16 v[10:13], v[188:191], v[220:223], v[12:15]
	v_mfma_f32_16x16x32_bf16 v[6:9], v[196:199], v[220:223], v[6:9]
	v_mfma_f32_16x16x32_bf16 v[60:63], v[192:195], v[168:171], v[60:63]
	v_mfma_f32_16x16x32_bf16 v[56:59], v[200:203], v[168:171], v[56:59]
	v_mfma_f32_16x16x32_bf16 v[44:47], v[192:195], v[208:211], v[44:47]
	v_mfma_f32_16x16x32_bf16 v[40:43], v[200:203], v[208:211], v[40:43]
	v_mfma_f32_16x16x32_bf16 v[28:31], v[192:195], v[216:219], v[28:31]
	v_mfma_f32_16x16x32_bf16 v[24:27], v[200:203], v[216:219], v[24:27]
	v_mfma_f32_16x16x32_bf16 v[12:15], v[192:195], v[224:227], v[10:13]
	v_mfma_f32_16x16x32_bf16 v[8:11], v[200:203], v[224:227], v[6:9]
	s_setprio 0
	s_barrier
	s_add_u32 s26, s26, 0x100
	s_addc_u32 s27, s27, 0
	s_add_u32 s69, s69, 0x100
	s_addc_u32 s70, s70, 0
	s_cmp_ge_i32 s8, s63
	s_cbranch_scc0 .LBB0_1018
